# one static priority raise for the younger wave half (waves 4-7) before each attention main loop, reset at loop exit
# speedup vs baseline: 1.0038x; 1.0012x over previous
; __device__ __forceinline__ int v_st(int k, int c) { const int kk = (k & ~0xC) | ((k & 4) << 1) | ((k & 8) >> 1); return ((kk >> 3) * 4 + (c >> 5)) * 512 + ((kk & 7) * 32 + (c & 31)) * 2; }
; __device__ __forceinline__ int v_rd_base(int lane) { return ((lane & 3) << 3) | (((lane >> 2) & 3) << 6) | (((lane >> 4) & 1) << 5) | (((lane >> 5) & 1) << 8); }
; #define SLOAD(i, j) do { const long rb_ = KROW(j); sr_[i].vs0 = *(const bf16x8*)(a.V + (rb_ + sr) * LDV + sc); sr_[i].vs1 = *(const bf16x8*)(a.V + (rb_ + 32 + sr) * LDV + sc); \
;     _Pragma("unroll") for (int c_ = 0; c_ < KCH; ++c_) sr_[i].ks[c_] = *(const bf16x8*)(kptr[c_] + rb_ * kld[c_]); } while (0)
; template <int DQK, int DK1, int LDQ, int LDK, int LDKR, int LDV, int NQL, int SDEPTH>
; __device__ __forceinline__ void attn_core(const AttnArgs& a, char* lds, f32x16 (&o)[4]) {
;     ...
;     { const bf16_t* Qw = a.Q + (long)(wid * 32 + r32) * LDQ + hi * 8;
; #pragma unroll
;       for (int d0 = 0; d0 < NQR; ++d0) qr[d0] = *(const bf16x8*)(Qw + d0 * 16);
; #pragma unroll
;       for (int d0 = NQR; d0 < ND0; ++d0) *(bf16x8*)(QL + (d0 - NQR) * 8192) = *(const bf16x8*)(Qw + d0 * 16); }
;     const int sr = tid >> 4, sc = (tid & 15) * 8, vst0 = v_st(sr, sc), vst1 = v_st(32 + sr, sc);
;     const int vb0 = (int)(uintptr_t)V_lds + v_rd_base(lane);
;     const bf16_t* kptr[KCH]; int kld[KCH], kwo[KCH];
; #pragma unroll
;     for (int c = 0; c < KCH; ++c) { const int idx = tid + c * 512, kr_ = idx / CPR, kc = (idx % CPR) * 8;
;         if (kc < DK1) { kptr[c] = a.Kn + (long)kr_ * LDK + kc; kld[c] = LDK; } else { kptr[c] = a.Kr + (long)kr_ * LDKR + (kc - DK1); kld[c] = LDKR; }
;         kwo[c] = kr_ * KP + ((kc * 2) ^ ((kr_ & 7) << 4)); }
;     struct { bf16x8 vs0, vs1, ks[KCH]; } sr_[SDEPTH];
;     int kb[4];
; #pragma unroll
;     for (int m = 0; m < 4; ++m) kb[m] = r32 * KP + ((m * 32 + hi * 16) ^ ((r32 & 7) << 4));
;     ...
;     f32x16 pA0, pA1, pB0, pB1; float mnA, mnB, alA, alB; bf16x8 pa0, pa1, pa2, pa3; const int NT = a.NT;
;     constexpr int SE = 0, SO = SDEPTH - 1;
;     SLOAD(SE, 0); asm volatile("s_waitcnt vmcnt(0)" ::: "memory"); SWRITE(0, SE); __syncthreads();
.LBB0_170:
	v_mov_b32_e32 v14, v159
	s_xor_b64 s[94:95], s[14:15], -1
	s_lshl_b64 s[14:15], s[12:13], 1
	s_add_u32 s12, s87, s14
	v_ashrrev_i32_e32 v0, 31, v14
	v_lshrrev_b32_e32 v0, 29, v0
	s_addc_u32 s13, s68, s15
	v_add_u32_e32 v0, v14, v0
	s_add_u32 s14, s28, s14
	v_ashrrev_i32_e32 v16, 3, v0
	v_and_b32_e32 v0, -8, v0
	s_addc_u32 s15, s29, s15
	v_sub_u32_e32 v17, v14, v0
	v_ashrrev_i32_e32 v164, 4, v14
	v_lshlrev_b32_e32 v0, 3, v17
	v_mov_b64_e32 v[2:3], s[14:15]
	v_mad_i64_i32 v[2:3], s[14:15], v16, s9, v[2:3]
	v_ashrrev_i32_e32 v1, 31, v0
	v_ashrrev_i32_e32 v165, 31, v164
	v_lshlrev_b32_e32 v15, 3, v14
	v_lshl_add_u64 v[166:167], v[0:1], 1, v[2:3]
	v_lshl_add_u64 v[0:1], v[164:165], 0, s[18:19]
	v_mov_b64_e32 v[50:51], s[20:21]
	v_and_b32_e32 v4, 0x78, v15
	v_mad_u64_u32 v[2:3], s[14:15], v0, s9, v[50:51]
	v_mad_i32_i24 v3, v1, s9, v3
	v_lshlrev_b32_e32 v48, 1, v4
	v_mov_b32_e32 v49, v97
	v_lshl_add_u64 v[168:169], v[164:165], 0, 32
	v_lshl_add_u64 v[0:1], v[2:3], 0, v[48:49]
	v_lshl_add_u64 v[2:3], v[168:169], 0, s[18:19]
	v_mad_u64_u32 v[4:5], s[14:15], v2, s9, v[50:51]
	v_mad_i32_i24 v5, v3, s9, v5
	v_lshl_add_u64 v[4:5], v[4:5], 0, v[48:49]
	global_load_dwordx4 v[0:3], v[0:1], off
	s_nop 0
	global_load_dwordx4 v[4:7], v[4:5], off
	v_ashrrev_i32_e32 v12, 1, v14
	v_lshl_add_u64 v[8:9], v[166:167], 0, s[22:23]
	v_bfi_b32 v18, s33, v12, v14
	v_mov_b64_e32 v[12:13], s[12:13]
	global_load_dwordx4 v[8:11], v[8:9], off
	v_mad_i64_i32 v[12:13], s[12:13], v18, s9, v[12:13]
	v_lshrrev_b32_e32 v18, 1, v14
	v_and_b32_e32 v96, 16, v18
	v_lshl_add_u64 v[12:13], v[12:13], 0, v[96:97]
	global_load_dwordx4 v[110:113], v[12:13], off
	global_load_dwordx4 v[106:109], v[12:13], off offset:32
	global_load_dwordx4 v[102:105], v[12:13], off offset:64
	global_load_dwordx4 v[98:101], v[12:13], off offset:96
	v_and_b32_e32 v18, 0xfffff0, v164
	v_lshlrev_b32_e32 v19, 1, v164
	v_lshrrev_b32_e32 v20, 1, v164
	v_and_b32_e32 v21, 3, v164
	v_add_u32_e32 v22, 32, v164
	v_and_or_b32 v18, v19, 8, v18
	v_and_or_b32 v19, v20, 4, v21
	v_and_b32_e32 v20, 0xfffff0, v22
	v_lshlrev_b32_e32 v21, 1, v22
	v_bfe_u32 v15, v15, 5, 2
	v_lshrrev_b32_e32 v18, 1, v18
	v_and_or_b32 v20, v21, 8, v20
	v_and_b32_e32 v68, 31, v14
	v_lshlrev_b32_e32 v52, 4, v14
	v_or_b32_e32 v12, v18, v15
	v_lshrrev_b32_e32 v13, 1, v20
	v_lshlrev_b32_e32 v53, 7, v68
	v_and_b32_e32 v54, 0x70, v52
	v_and_b32_e32 v23, 48, v52
	v_lshlrev_b32_e32 v19, 6, v19
	v_lshlrev_b32_e32 v12, 9, v12
	v_or_b32_e32 v13, v13, v15
	v_bitop3_b32 v22, v96, v53, v54 bitop3:0xde
	v_lshlrev_b32_e32 v18, 7, v16
	v_bitop3_b32 v15, v16, v17, 7 bitop3:0x6c
	v_lshlrev_b32_e32 v13, 9, v13
	v_or3_b32 v12, v12, v19, v23
	v_lshl_add_u32 v15, v15, 4, v18
	v_or3_b32 v13, v13, v19, v23
	v_add_u32_e32 v181, 0, v12
	v_add_u32_e32 v186, 0, v22
	v_add_u32_e32 v182, 0, v15
	v_add_u32_e32 v184, 0, v13
	s_waitcnt vmcnt(0)
	v_and_b32_e32 v69, 63, v14
	v_lshl_add_u64 v[64:65], v[164:165], 0, s[88:89]
	v_mad_u64_u32 v[66:67], s[12:13], v64, s9, v[50:51]
	v_mad_i32_i24 v67, v65, s9, v67
	v_lshl_add_u64 v[60:61], v[166:167], 0, s[78:79]
	v_lshl_add_u64 v[64:65], v[66:67], 0, v[48:49]
	s_cmp_lg_u32 0, -1
	s_cselect_b32 s14, 0, 0
	s_waitcnt vmcnt(0)
	ds_write_b128 v181, v[0:3]
	s_waitcnt vmcnt(5)
	ds_write_b128 v184, v[4:7]
	s_waitcnt vmcnt(4)
	ds_write_b128 v182, v[8:11] offset:32768
	s_waitcnt lgkmcnt(0)
	s_barrier
	ds_read_b128 v[0:3], v186 offset:32768
	ds_read_b128 v[4:7], v186 offset:36864
	s_waitcnt vmcnt(3) lgkmcnt(1)
	v_mfma_f32_32x32x16_bf16 v[32:47], v[0:3], v[110:113], 0
	v_or_b32_e32 v0, 32, v96
	v_bitop3_b32 v0, v0, v53, v54 bitop3:0xde
	v_add_u32_e32 v188, 0, v0
	ds_read_b128 v[0:3], v188 offset:32768
	v_and_b32_e32 v8, 0x3fffffc0, v14
	v_lshl_add_u32 v161, v8, 2, 0
	v_lshlrev_b32_e32 v8, 3, v69
	s_waitcnt lgkmcnt(1)
	v_mfma_f32_32x32x16_bf16 v[16:31], v[4:7], v[110:113], 0
	ds_read_b128 v[4:7], v188 offset:36864
	s_mov_b32 s37, s36
	s_mov_b32 s38, s36
	s_mov_b32 s39, s36
	s_mov_b32 s40, s36
	s_mov_b32 s41, s36
	s_mov_b32 s42, s36
	s_waitcnt vmcnt(2) lgkmcnt(1)
	v_mfma_f32_32x32x16_bf16 v[32:47], v[0:3], v[106:109], v[32:47]
	v_or_b32_e32 v0, 64, v96
	v_bitop3_b32 v0, v0, v53, v54 bitop3:0xde
	v_add_u32_e32 v190, 0, v0
	ds_read_b128 v[0:3], v190 offset:32768
	s_mov_b32 s43, s36
	s_mov_b32 s44, s36
	s_mov_b32 s45, s36
	s_waitcnt lgkmcnt(1)
	v_mfma_f32_32x32x16_bf16 v[16:31], v[4:7], v[106:109], v[16:31]
	v_and_b32_e32 v4, 0xc0, v52
	v_lshlrev_b32_e32 v5, 1, v14
	v_and_or_b32 v4, v8, 24, v4
	v_and_b32_e32 v5, 32, v5
	v_and_b32_e32 v6, 0x100, v8
	v_or3_b32 v70, v4, v5, v6
	ds_read_b128 v[4:7], v190 offset:36864
	s_waitcnt vmcnt(1) lgkmcnt(1)
	v_mfma_f32_32x32x16_bf16 v[32:47], v[0:3], v[102:105], v[32:47]
	v_or_b32_e32 v0, 0x60, v96
	v_bitop3_b32 v0, v0, v53, v54 bitop3:0xde
	v_add_u32_e32 v192, 0, v0
	ds_read_b128 v[0:3], v192 offset:32768
	ds_read_b128 v[52:55], v192 offset:36864
	s_mov_b32 s46, s36
	s_mov_b32 s47, s36
	s_waitcnt lgkmcnt(2)
	v_mfma_f32_32x32x16_bf16 v[16:31], v[4:7], v[102:105], v[16:31]
	s_mov_b32 s48, s36
	s_mov_b32 s49, s36
	s_mov_b32 s50, s36
	s_mov_b32 s51, s36
	v_add_u32_e32 v180, s14, v70
	v_lshl_add_u64 v[170:171], s[20:21], 0, v[48:49]
	s_mov_b32 s52, 4
	s_waitcnt vmcnt(0) lgkmcnt(1)
; #define SLOAD(i, j) do { const long rb_ = KROW(j); sr_[i].vs0 = *(const bf16x8*)(a.V + (rb_ + sr) * LDV + sc); sr_[i].vs1 = *(const bf16x8*)(a.V + (rb_ + 32 + sr) * LDV + sc); \
;     _Pragma("unroll") for (int c_ = 0; c_ < KCH; ++c_) sr_[i].ks[c_] = *(const bf16x8*)(kptr[c_] + rb_ * kld[c_]); } while (0)
; #define SWRITE(b, i) do { *(bf16x8*)(V_lds + (b) * SHM_V + vst0) = sr_[i].vs0; *(bf16x8*)(V_lds + (b) * SHM_V + vst1) = sr_[i].vs1; \
;     _Pragma("unroll") for (int c_ = 0; c_ < KCH; ++c_) *(bf16x8*)(K_lds + (b) * SHM_K + kwo[c_]) = sr_[i].ks[c_]; } while (0)
; __device__ __forceinline__ void partialSM(f32x16& p0, f32x16& p1, float& m_reg, float& mn, float& alpha, const float C, const float thr) {
;     float pmax = p0[0];
; #pragma unroll
;     for (int r = 1; r < 16; ++r) pmax = fmaxf(pmax, p0[r]);
; #pragma unroll
;     for (int r = 0; r < 16; ++r) pmax = fmaxf(pmax, p1[r]);
;     { auto rr = __builtin_amdgcn_permlane32_swap(__float_as_uint(pmax), __float_as_uint(pmax), false, false);
;       pmax = fmaxf(__uint_as_float(rr[0]), __uint_as_float(rr[1])); }
;     if (__builtin_expect(__all(pmax - m_reg <= thr), 1)) { mn = m_reg; alpha = 1.f; }
;     else { mn = fmaxf(m_reg, pmax); alpha = __builtin_amdgcn_exp2f((m_reg - mn) * C); m_reg = mn; }
;     const float mnC = -mn * C;
; #pragma unroll
;     for (int r = 0; r < 16; ++r) p0[r] = fmaf(p0[r], C, mnC);
; #pragma unroll
;     for (int r = 0; r < 16; ++r) p1[r] = fmaf(p1[r], C, mnC);
; #pragma unroll
;     for (int r = 0; r < 16; ++r) p0[r] = __builtin_amdgcn_exp2f(p0[r]);
; }
; template <int DQK, int DK1, int LDQ, int LDK, int LDKR, int LDV, int NQL, int SDEPTH>
; __device__ __forceinline__ void attn_core(const AttnArgs& a, char* lds, f32x16 (&o)[4]) {
;     ...
;     SLOAD(SE, 0); asm volatile("s_waitcnt vmcnt(0)" ::: "memory"); SWRITE(0, SE); __syncthreads();
;     QKT(pA0, pA1, K_lds); partialSM(pA0, pA1, m_reg, mnA, alA, a.C, a.thr);
;     SLOAD(SO, 1); if (SDEPTH == 2 && 2 < NT) SLOAD(SE, 2);
;     SWRITE(1, SO); __syncthreads();
	v_mfma_f32_32x32x16_bf16 v[32:47], v[0:3], v[98:101], v[32:47]
	v_mov_b64_e32 v[0:1], s[36:37]
	v_mov_b64_e32 v[14:15], s[50:51]
	v_mov_b64_e32 v[2:3], s[38:39]
	v_mov_b64_e32 v[4:5], s[40:41]
	v_mov_b64_e32 v[6:7], s[42:43]
	v_mov_b64_e32 v[8:9], s[44:45]
	v_mov_b64_e32 v[10:11], s[46:47]
	s_waitcnt lgkmcnt(0)
	v_mfma_f32_32x32x16_bf16 v[16:31], v[52:55], v[98:101], v[16:31]
	s_nop 2
	v_max_f32_e32 v52, v33, v33
	v_max_f32_e32 v53, v32, v32
	v_max_f32_e32 v52, v53, v52
	v_max3_f32 v52, v52, v34, v35
	v_max3_f32 v52, v52, v36, v37
	v_max3_f32 v52, v52, v38, v39
	v_max3_f32 v52, v52, v40, v41
	v_max3_f32 v52, v52, v42, v43
	v_max3_f32 v52, v52, v44, v45
	v_max3_f32 v52, v52, v46, v47
	v_max3_f32 v52, v52, v16, v17
	v_max3_f32 v71, v52, v18, v19
	v_lshl_add_u64 v[52:53], v[164:165], 0, s[24:25]
	v_mad_u64_u32 v[54:55], s[12:13], v52, s9, v[50:51]
	v_mad_i32_i24 v55, v53, s9, v55
	v_lshl_add_u64 v[52:53], v[54:55], 0, v[48:49]
	v_lshl_add_u64 v[54:55], v[168:169], 0, s[24:25]
	v_mad_u64_u32 v[56:57], s[12:13], v54, s9, v[50:51]
	v_mad_i32_i24 v57, v55, s9, v57
	v_lshl_add_u64 v[56:57], v[56:57], 0, v[48:49]
	global_load_dwordx4 v[52:55], v[52:53], off
	s_nop 0
	global_load_dwordx4 v[56:59], v[56:57], off
	v_mov_b64_e32 v[12:13], s[48:49]
	global_load_dwordx4 v[60:63], v[60:61], off
	v_lshl_add_u32 v177, v68, 2, v161
	global_load_dwordx4 v[114:117], v[64:65], off
	v_lshl_add_u64 v[64:65], v[168:169], 0, s[88:89]
	v_mad_u64_u32 v[50:51], s[12:13], v64, s9, v[50:51]
	v_mad_i32_i24 v51, v65, s9, v51
	v_lshl_add_u64 v[50:51], v[50:51], 0, v[48:49]
	v_lshl_add_u64 v[64:65], v[166:167], 0, s[90:91]
	global_load_dwordx4 v[118:121], v[50:51], off
	global_load_dwordx4 v[122:125], v[64:65], off
	v_max3_f32 v50, v71, v20, v21
	v_max3_f32 v50, v50, v22, v23
	v_max3_f32 v50, v50, v24, v25
	v_max3_f32 v50, v50, v26, v27
	v_max3_f32 v50, v50, v28, v29
	v_max3_f32 v50, v50, v30, v31
	v_mov_b32_e32 v51, v50
	s_nop 1
	v_permlane32_swap_b32_e32 v50, v51
	v_max_f32_e32 v51, v51, v51
	v_max_f32_e32 v50, v50, v50
	v_max_f32_e32 v50, v50, v51
	v_add_f32_e32 v51, 0x7149f2ca, v50
	v_max_f32_e32 v50, 0xf149f2ca, v50
	v_cmp_ge_f32_e32 vcc, s76, v51
	v_sub_f32_e32 v51, 0xf149f2ca, v50
	v_mul_f32_e32 v51, 0x3e38aa3b, v51
	v_exp_f32_e32 v51, v51
	s_cmp_eq_u64 vcc, exec
	s_cselect_b64 vcc, -1, 0
	v_cndmask_b32_e32 v142, v50, v193, vcc
	v_mul_f32_e32 v50, 0xbe38aa3b, v142
	v_cndmask_b32_e64 v194, v51, 1.0, vcc
	v_mov_b32_e32 v51, v50
	v_fmamk_f32 v32, v32, 0x3e38aa3b, v50
	v_fmamk_f32 v33, v33, 0x3e38aa3b, v50
	v_fmamk_f32 v34, v34, 0x3e38aa3b, v50
	v_fmamk_f32 v35, v35, 0x3e38aa3b, v50
	v_fmamk_f32 v36, v36, 0x3e38aa3b, v50
	v_fmamk_f32 v37, v37, 0x3e38aa3b, v50
	v_fmamk_f32 v38, v38, 0x3e38aa3b, v50
	v_fmamk_f32 v39, v39, 0x3e38aa3b, v50
	v_fmamk_f32 v40, v40, 0x3e38aa3b, v50
	v_fmamk_f32 v41, v41, 0x3e38aa3b, v50
	v_fmamk_f32 v42, v42, 0x3e38aa3b, v50
	v_fmamk_f32 v43, v43, 0x3e38aa3b, v50
	v_fmamk_f32 v44, v44, 0x3e38aa3b, v50
	v_fmamk_f32 v45, v45, 0x3e38aa3b, v50
	v_fmamk_f32 v46, v46, 0x3e38aa3b, v50
	v_fmac_f32_e32 v51, 0x3e38aa3b, v47
	v_exp_f32_e32 v217, v32
	v_exp_f32_e32 v219, v33
	v_exp_f32_e32 v208, v34
	v_exp_f32_e32 v218, v35
	v_exp_f32_e32 v153, v36
	v_exp_f32_e32 v216, v37
	v_exp_f32_e32 v152, v38
	v_exp_f32_e32 v202, v39
	v_exp_f32_e32 v149, v40
	v_exp_f32_e32 v151, v41
	v_exp_f32_e32 v147, v42
	v_exp_f32_e32 v150, v43
	v_exp_f32_e32 v145, v44
	v_exp_f32_e32 v148, v45
	v_exp_f32_e32 v144, v46
	v_exp_f32_e32 v146, v51
	v_pk_fma_f32 v[132:133], v[30:31], s[8:9], v[50:51] op_sel_hi:[1,0,0]
	v_pk_fma_f32 v[134:135], v[28:29], s[8:9], v[50:51] op_sel_hi:[1,0,0]
	v_pk_fma_f32 v[140:141], v[26:27], s[8:9], v[50:51] op_sel_hi:[1,0,0]
	v_pk_fma_f32 v[126:127], v[24:25], s[8:9], v[50:51] op_sel_hi:[1,0,0]
	v_pk_fma_f32 v[128:129], v[22:23], s[8:9], v[50:51] op_sel_hi:[1,0,0]
	v_pk_fma_f32 v[130:131], v[20:21], s[8:9], v[50:51] op_sel_hi:[1,0,0]
	v_pk_fma_f32 v[136:137], v[18:19], s[8:9], v[50:51] op_sel_hi:[1,0,0]
	v_pk_fma_f32 v[138:139], v[16:17], s[8:9], v[50:51] op_sel_hi:[1,0,0]
	s_waitcnt vmcnt(5)
	ds_write_b128 v181, v[52:55] offset:16384
	s_waitcnt vmcnt(4)
	ds_write_b128 v184, v[56:59] offset:16384
	s_waitcnt vmcnt(3)
	ds_write_b128 v182, v[60:63] offset:40960
	s_addk_i32 s14, 0x4000
	v_mov_b64_e32 v[30:31], v[14:15]
	v_mov_b64_e32 v[46:47], v[14:15]
	v_mov_b64_e32 v[62:63], v[14:15]
	v_cmp_gt_u32_e64 s[12:13], 32, v69
	v_add_u32_e32 v179, s14, v70
	v_mov_b32_e32 v178, 0
	v_mov_b64_e32 v[28:29], v[12:13]
	v_mov_b64_e32 v[26:27], v[10:11]
	v_mov_b64_e32 v[24:25], v[8:9]
	v_mov_b64_e32 v[22:23], v[6:7]
	v_mov_b64_e32 v[20:21], v[4:5]
	v_mov_b64_e32 v[18:19], v[2:3]
	v_mov_b64_e32 v[16:17], v[0:1]
	v_mov_b64_e32 v[44:45], v[12:13]
	v_mov_b64_e32 v[42:43], v[10:11]
	v_mov_b64_e32 v[40:41], v[8:9]
	v_mov_b64_e32 v[38:39], v[6:7]
	v_mov_b64_e32 v[36:37], v[4:5]
	v_mov_b64_e32 v[34:35], v[2:3]
	v_mov_b64_e32 v[32:33], v[0:1]
	v_mov_b64_e32 v[60:61], v[12:13]
	v_mov_b64_e32 v[58:59], v[10:11]
	v_mov_b64_e32 v[56:57], v[8:9]
	v_mov_b64_e32 v[54:55], v[6:7]
	v_mov_b64_e32 v[52:53], v[4:5]
	v_mov_b64_e32 v[50:51], v[2:3]
	v_mov_b64_e32 v[48:49], v[0:1]
	v_readfirstlane_b32 s98, v159
	s_nop 3
	s_cmp_gt_u32 s98, 0xff
	s_cbranch_scc0 .Lsprio_d
	s_setprio 1

; #define SBAR() __builtin_amdgcn_sched_barrier(0)
; __device__ __forceinline__ void finishSM(f32x16& p0, f32x16& p1, float alpha, float& l_reg, bf16x8& pa0, bf16x8& pa1, bf16x8& pa2, bf16x8& pa3) {
; #pragma unroll
;     for (int r = 0; r < 16; ++r) p1[r] = __builtin_amdgcn_exp2f(p1[r]);
;     float ps = 0;
; #pragma unroll
;     for (int r = 0; r < 16; ++r) ps += p0[r];
; #pragma unroll
;     for (int r = 0; r < 16; ++r) ps += p1[r];
;     { auto rr = __builtin_amdgcn_permlane32_swap(__float_as_uint(ps), __float_as_uint(ps), false, false);
;       ps = __uint_as_float(rr[0]) + __uint_as_float(rr[1]); }
;     l_reg = l_reg * alpha + ps;
;     ...
;     PK4(p0, 0, pa0); PK4(p0, 8, pa1); PK4(p1, 0, pa2); PK4(p1, 8, pa3);
;     ...
; }
; template <int DQK, int DK1, int LDQ, int LDK, int LDKR, int LDV, int NQL, int SDEPTH>
; __device__ __forceinline__ void attn_core(const AttnArgs& a, char* lds, f32x16 (&o)[4]) {
;     ...
;     SBAR(); QKT(pB0, pB1, K_lds + SHM_K);
;     finishSM(pA0, pA1, alA, l_reg, pa0, pa1, pa2, pa3); SBAR();
;     pv_d0(o, vb0, pa0, pa1, pa2, pa3); partialSM(pB0, pB1, m_reg, mnB, alB, a.C, a.thr);
.LBB0_183:
	s_setprio 0
	ds_read_b128 v[64:67], v186 offset:40960
	ds_read_b128 v[68:71], v186 offset:45056
	v_exp_f32_e32 v118, v140
	v_exp_f32_e32 v119, v141
	v_exp_f32_e32 v120, v134
	s_waitcnt lgkmcnt(1)
	v_mfma_f32_32x32x16_bf16 v[80:95], v[64:67], v[110:113], 0
	v_exp_f32_e32 v121, v135
	v_exp_f32_e32 v122, v132
	v_exp_f32_e32 v123, v133
	s_waitcnt lgkmcnt(0)
	v_mfma_f32_32x32x16_bf16 v[64:79], v[68:71], v[110:113], 0
	ds_read_b128 v[110:113], v188 offset:40960
	ds_read_b128 v[114:117], v188 offset:45056
	s_waitcnt lgkmcnt(1)
	v_mfma_f32_32x32x16_bf16 v[80:95], v[110:113], v[106:109], v[80:95]
	s_waitcnt lgkmcnt(0)
	v_mfma_f32_32x32x16_bf16 v[64:79], v[114:117], v[106:109], v[64:79]
	ds_read_b128 v[106:109], v190 offset:40960
	ds_read_b128 v[110:113], v190 offset:45056
	v_exp_f32_e32 v114, v128
	v_exp_f32_e32 v115, v129
	v_exp_f32_e32 v116, v126
	v_exp_f32_e32 v117, v127
	s_waitcnt lgkmcnt(1)
	v_mfma_f32_32x32x16_bf16 v[80:95], v[106:109], v[102:105], v[80:95]
	s_waitcnt lgkmcnt(0)
	v_mfma_f32_32x32x16_bf16 v[64:79], v[110:113], v[102:105], v[64:79]
	ds_read_b128 v[102:105], v192 offset:40960
	ds_read_b128 v[106:109], v192 offset:45056
	v_exp_f32_e32 v110, v136
	v_exp_f32_e32 v111, v137
	v_exp_f32_e32 v112, v130
	v_exp_f32_e32 v113, v131
	s_waitcnt lgkmcnt(1)
	v_mfma_f32_32x32x16_bf16 v[80:95], v[102:105], v[98:101], v[80:95]
	s_waitcnt lgkmcnt(0)
	v_mfma_f32_32x32x16_bf16 v[64:79], v[106:109], v[98:101], v[64:79]
	v_add_f32_e32 v98, 0, v217
	v_add_f32_e32 v98, v219, v98
	v_add_f32_e32 v98, v208, v98
	v_add_f32_e32 v98, v218, v98
	v_add_f32_e32 v98, v153, v98
	v_add_f32_e32 v98, v216, v98
	v_add_f32_e32 v98, v152, v98
	v_add_f32_e32 v98, v202, v98
	v_add_f32_e32 v98, v149, v98
	v_add_f32_e32 v98, v151, v98
	v_add_f32_e32 v98, v147, v98
	v_add_f32_e32 v98, v150, v98
	v_exp_f32_e32 v108, v138
	v_add_f32_e32 v98, v145, v98
	v_exp_f32_e32 v109, v139
	v_add_f32_e32 v98, v148, v98
	v_add_f32_e32 v98, v144, v98
	v_add_f32_e32 v98, v146, v98
	v_add_f32_e32 v98, v108, v98
	v_add_f32_e32 v98, v109, v98
	v_add_f32_e32 v98, v110, v98
	v_add_f32_e32 v98, v111, v98
	v_add_f32_e32 v98, v112, v98
	v_add_f32_e32 v98, v113, v98
	v_add_f32_e32 v98, v114, v98
	v_add_f32_e32 v98, v115, v98
	v_add_f32_e32 v98, v116, v98
	v_add_f32_e32 v98, v117, v98
	v_add_f32_e32 v98, v118, v98
	v_add_f32_e32 v98, v119, v98
	v_add_f32_e32 v98, v120, v98
	v_add_f32_e32 v98, v121, v98
	v_add_f32_e32 v98, v122, v98
	v_add_f32_e32 v98, v123, v98
	v_mov_b32_e32 v99, v98
	v_cvt_pk_bf16_f32 v100, v217, v219
	v_cvt_pk_bf16_f32 v101, v208, v218
	v_cvt_pk_bf16_f32 v102, v153, v216
	v_cvt_pk_bf16_f32 v103, v152, v202
	s_nop 1
	v_permlane32_swap_b32_e32 v98, v99
	v_permlane32_swap_b32_e32 v100, v102
	v_permlane32_swap_b32_e32 v101, v103
	v_cvt_pk_bf16_f32 v104, v149, v151
	v_cvt_pk_bf16_f32 v105, v147, v150
	v_cvt_pk_bf16_f32 v106, v145, v148
	v_cvt_pk_bf16_f32 v107, v144, v146
	v_cvt_pk_bf16_f32 v108, v108, v109
	v_cvt_pk_bf16_f32 v109, v110, v111
	v_cvt_pk_bf16_f32 v110, v112, v113
	v_cvt_pk_bf16_f32 v111, v114, v115
	v_cvt_pk_bf16_f32 v112, v116, v117
	v_cvt_pk_bf16_f32 v113, v118, v119
	v_cvt_pk_bf16_f32 v114, v120, v121
	v_cvt_pk_bf16_f32 v115, v122, v123
	s_nop 0
	v_permlane32_swap_b32_e32 v104, v106
	v_permlane32_swap_b32_e32 v105, v107
	v_permlane32_swap_b32_e32 v108, v110
	v_permlane32_swap_b32_e32 v109, v111
	v_permlane32_swap_b32_e32 v112, v114
	v_permlane32_swap_b32_e32 v113, v115
	ds_read_b64_tr_b16 v[116:117], v180 offset:0
	ds_read_b64_tr_b16 v[118:119], v180 offset:0x800
	ds_read_b64_tr_b16 v[120:121], v180 offset:0x1000
	ds_read_b64_tr_b16 v[122:123], v180 offset:0x1800
	ds_read_b64_tr_b16 v[124:125], v180 offset:0x2000
	ds_read_b64_tr_b16 v[126:127], v180 offset:0x2800
	ds_read_b64_tr_b16 v[128:129], v180 offset:0x3000
	ds_read_b64_tr_b16 v[130:131], v180 offset:0x3800
	s_waitcnt lgkmcnt(0)
	s_nop 0
	v_mfma_f32_32x32x16_bf16 v[48:63], v[100:103], v[116:119], v[48:63]
	ds_read_b64_tr_b16 v[116:117], v180 offset:0x200
	ds_read_b64_tr_b16 v[118:119], v180 offset:0xa00
	v_mfma_f32_32x32x16_bf16 v[48:63], v[104:107], v[120:123], v[48:63]
	ds_read_b64_tr_b16 v[120:121], v180 offset:0x1200
	ds_read_b64_tr_b16 v[122:123], v180 offset:0x1a00
	v_mfma_f32_32x32x16_bf16 v[48:63], v[108:111], v[124:127], v[48:63]
	ds_read_b64_tr_b16 v[124:125], v180 offset:0x2200
	ds_read_b64_tr_b16 v[126:127], v180 offset:0x2a00
	v_mfma_f32_32x32x16_bf16 v[48:63], v[112:115], v[128:131], v[48:63]
	ds_read_b64_tr_b16 v[128:129], v180 offset:0x3200
	ds_read_b64_tr_b16 v[130:131], v180 offset:0x3a00
	s_waitcnt lgkmcnt(0)
; #define RESC(al) do { if (__any((al) < 1.f)) { if (hi == 0) al_l[r32] = (al); asm volatile("s_waitcnt lgkmcnt(0)" ::: "memory"); \
;     _Pragma("unroll") for (int d = 0; d < 4; ++d) _Pragma("unroll") for (int r = 0; r < 16; ++r) o[d][r] *= al_l[crow(r, hi)]; } } while (0)
; __device__ __forceinline__ void partialSM(f32x16& p0, f32x16& p1, float& m_reg, float& mn, float& alpha, const float C, const float thr) {
;     float pmax = p0[0];
; #pragma unroll
;     for (int r = 1; r < 16; ++r) pmax = fmaxf(pmax, p0[r]);
; #pragma unroll
;     for (int r = 0; r < 16; ++r) pmax = fmaxf(pmax, p1[r]);
;     { auto rr = __builtin_amdgcn_permlane32_swap(__float_as_uint(pmax), __float_as_uint(pmax), false, false);
;       pmax = fmaxf(__uint_as_float(rr[0]), __uint_as_float(rr[1])); }
;     if (__builtin_expect(__all(pmax - m_reg <= thr), 1)) { mn = m_reg; alpha = 1.f; }
;     else { mn = fmaxf(m_reg, pmax); alpha = __builtin_amdgcn_exp2f((m_reg - mn) * C); m_reg = mn; }
; template <int DQK, int DK1, int LDQ, int LDK, int LDKR, int LDV, int NQL, int SDEPTH>
; __device__ __forceinline__ void attn_core(const AttnArgs& a, char* lds, f32x16 (&o)[4]) {
;     ...
;     pv_d0(o, vb0, pa0, pa1, pa2, pa3); partialSM(pB0, pB1, m_reg, mnB, alB, a.C, a.thr);
;     __syncthreads(); RESC(alB);
	v_mfma_f32_32x32x16_bf16 v[32:47], v[100:103], v[116:119], v[32:47]
	ds_read_b64_tr_b16 v[116:117], v180 offset:0x400
	ds_read_b64_tr_b16 v[118:119], v180 offset:0xc00
	v_mfma_f32_32x32x16_bf16 v[32:47], v[104:107], v[120:123], v[32:47]
	ds_read_b64_tr_b16 v[120:121], v180 offset:0x1400
	ds_read_b64_tr_b16 v[122:123], v180 offset:0x1c00
	v_mfma_f32_32x32x16_bf16 v[32:47], v[108:111], v[124:127], v[32:47]
	ds_read_b64_tr_b16 v[124:125], v180 offset:0x2400
	ds_read_b64_tr_b16 v[126:127], v180 offset:0x2c00
	v_mfma_f32_32x32x16_bf16 v[32:47], v[112:115], v[128:131], v[32:47]
	ds_read_b64_tr_b16 v[128:129], v180 offset:0x3400
	ds_read_b64_tr_b16 v[130:131], v180 offset:0x3c00
	s_waitcnt lgkmcnt(0)
	v_mfma_f32_32x32x16_bf16 v[16:31], v[100:103], v[116:119], v[16:31]
	ds_read_b64_tr_b16 v[116:117], v180 offset:0x600
	ds_read_b64_tr_b16 v[118:119], v180 offset:0xe00
	v_mfma_f32_32x32x16_bf16 v[16:31], v[104:107], v[120:123], v[16:31]
	ds_read_b64_tr_b16 v[120:121], v180 offset:0x1600
	ds_read_b64_tr_b16 v[122:123], v180 offset:0x1e00
	v_mfma_f32_32x32x16_bf16 v[16:31], v[108:111], v[124:127], v[16:31]
	ds_read_b64_tr_b16 v[124:125], v180 offset:0x2600
	ds_read_b64_tr_b16 v[126:127], v180 offset:0x2e00
	v_mfma_f32_32x32x16_bf16 v[16:31], v[112:115], v[128:131], v[16:31]
	ds_read_b64_tr_b16 v[128:129], v180 offset:0x3600
	ds_read_b64_tr_b16 v[130:131], v180 offset:0x3e00
	s_waitcnt lgkmcnt(0)
	v_mfma_f32_32x32x16_bf16 v[0:15], v[100:103], v[116:119], v[0:15]
	v_max_f32_e32 v100, v81, v81
	v_max_f32_e32 v101, v80, v80
	v_max_f32_e32 v100, v101, v100
	v_max3_f32 v100, v100, v82, v83
	v_max3_f32 v100, v100, v84, v85
	v_max3_f32 v100, v100, v86, v87
	v_max3_f32 v100, v100, v88, v89
	v_max3_f32 v100, v100, v90, v91
	v_max3_f32 v100, v100, v92, v93
	v_mfma_f32_32x32x16_bf16 v[0:15], v[104:107], v[120:123], v[0:15]
	v_max3_f32 v100, v100, v94, v95
	v_max3_f32 v100, v100, v64, v65
	v_max3_f32 v100, v100, v66, v67
	v_max3_f32 v100, v100, v68, v69
	v_max3_f32 v100, v100, v70, v71
	v_max3_f32 v100, v100, v72, v73
	v_max3_f32 v100, v100, v74, v75
	v_max3_f32 v100, v100, v76, v77
	v_mfma_f32_32x32x16_bf16 v[0:15], v[108:111], v[124:127], v[0:15]
	v_max3_f32 v100, v100, v78, v79
	v_mov_b32_e32 v101, v100
	s_nop 1
	v_permlane32_swap_b32_e32 v100, v101
	v_max_f32_e32 v101, v101, v101
	v_max_f32_e32 v100, v100, v100
	v_max_f32_e32 v100, v100, v101
	v_sub_f32_e32 v101, v100, v142
	v_cmp_ge_f32_e32 vcc, s76, v101
	v_max_f32_e32 v101, v142, v142
	v_max_f32_e32 v101, v101, v100
	v_mfma_f32_32x32x16_bf16 v[0:15], v[112:115], v[128:131], v[0:15]
	v_sub_f32_e32 v100, v142, v101
	v_mul_f32_e32 v100, 0x3e38aa3b, v100
	v_exp_f32_e32 v100, v100
	s_cmp_eq_u64 vcc, exec
	s_cselect_b64 s[14:15], -1, 0
	v_cndmask_b32_e64 v100, v100, 1.0, s[14:15]
	v_cmp_gt_f32_e32 vcc, 1.0, v100
	s_barrier
	s_cbranch_vccz .LBB0_187
	s_and_saveexec_b64 s[38:39], s[12:13]
	ds_write_b32 v177, v100 offset:49280
	s_or_b64 exec, exec, s[38:39]
	s_waitcnt lgkmcnt(0)
	v_add_u32_e32 v114, v161, v96
	ds_read_b128 v[102:105], v114 offset:49376
	ds_read_b128 v[106:109], v114 offset:49344
	ds_read_b128 v[110:113], v114 offset:49312
	ds_read_b128 v[114:117], v114 offset:49280
	s_waitcnt lgkmcnt(3)
	v_pk_mul_f32 v[60:61], v[60:61], v[102:103]
	s_waitcnt lgkmcnt(2)
	v_pk_mul_f32 v[56:57], v[56:57], v[106:107]
	s_waitcnt lgkmcnt(1)
	v_pk_mul_f32 v[52:53], v[52:53], v[110:111]
	v_pk_mul_f32 v[62:63], v[62:63], v[104:105]
	v_pk_mul_f32 v[58:59], v[58:59], v[108:109]
	v_pk_mul_f32 v[54:55], v[54:55], v[112:113]
	s_waitcnt lgkmcnt(0)
	v_pk_mul_f32 v[50:51], v[50:51], v[116:117]
	v_pk_mul_f32 v[48:49], v[48:49], v[114:115]
	v_pk_mul_f32 v[44:45], v[44:45], v[102:103]
	v_pk_mul_f32 v[40:41], v[40:41], v[106:107]
	v_pk_mul_f32 v[36:37], v[36:37], v[110:111]
	v_pk_mul_f32 v[46:47], v[46:47], v[104:105]
	v_pk_mul_f32 v[42:43], v[42:43], v[108:109]
	v_pk_mul_f32 v[38:39], v[38:39], v[112:113]
	v_pk_mul_f32 v[34:35], v[34:35], v[116:117]
	v_pk_mul_f32 v[32:33], v[32:33], v[114:115]
	v_pk_mul_f32 v[28:29], v[28:29], v[102:103]
	v_pk_mul_f32 v[24:25], v[24:25], v[106:107]
	v_pk_mul_f32 v[20:21], v[20:21], v[110:111]
	v_pk_mul_f32 v[30:31], v[30:31], v[104:105]
	v_pk_mul_f32 v[26:27], v[26:27], v[108:109]
	v_pk_mul_f32 v[22:23], v[22:23], v[112:113]
	v_pk_mul_f32 v[18:19], v[18:19], v[116:117]
	v_pk_mul_f32 v[16:17], v[16:17], v[114:115]
	v_pk_mul_f32 v[12:13], v[12:13], v[102:103]
	v_pk_mul_f32 v[8:9], v[8:9], v[106:107]
	v_pk_mul_f32 v[4:5], v[4:5], v[110:111]
	v_pk_mul_f32 v[14:15], v[14:15], v[104:105]
	v_pk_mul_f32 v[10:11], v[10:11], v[108:109]
	v_pk_mul_f32 v[6:7], v[6:7], v[112:113]
	v_pk_mul_f32 v[2:3], v[2:3], v[116:117]
	v_pk_mul_f32 v[0:1], v[0:1], v[114:115]

; __device__ __forceinline__ int tid_opaque() { int t = threadIdx.x; asm volatile("" : "+v"(t)); return t; }
; __device__ __forceinline__ int v_st(int k, int c) { const int kk = (k & ~0xC) | ((k & 4) << 1) | ((k & 8) >> 1); return ((kk >> 3) * 4 + (c >> 5)) * 512 + ((kk & 7) * 32 + (c & 31)) * 2; }
; __device__ __forceinline__ int v_rd_base(int lane) { return ((lane & 3) << 3) | (((lane >> 2) & 3) << 6) | (((lane >> 4) & 1) << 5) | (((lane >> 5) & 1) << 8); }
; template <int DQK, int DK1, int LDQ, int LDK, int LDKR, int LDV, int NQL, int SDEPTH>
; __device__ __forceinline__ void attn_core(const AttnArgs& a, char* lds, f32x16 (&o)[4]) {
;     constexpr int KP = DQK * 2, SHM_K = 64 * KP, SHM_V = 64 * 128 * 2, KCH = DQK / 64, CPR = DQK / 8, ND0 = DQK / 16;
;     const int tid = tid_opaque(), wid = tid >> 6, lane = tid & 63, r32 = lane & 31, hi = lane >> 5;
;     char* V_lds = lds; char* K_lds = lds + 2 * SHM_V;
;     float* wsf = (float*)(lds + 2 * SHM_V + 2 * SHM_K) + wid * 64; float* li_l = wsf; float* al_l = wsf + 32;
;     float m_reg = -1e30f, l_reg = 0.f;
; #pragma unroll
;     for (int d = 0; d < 4; ++d)
; #pragma unroll
;         for (int r = 0; r < 16; ++r) o[d][r] = 0.f;
;     constexpr int NQR = ND0 - NQL;
;     bf16x8 qr[NQR];
;     char* QL = lds + 2 * SHM_V + 2 * SHM_K + 2048 + tid * 16;
;     { const bf16_t* Qw = a.Q + (long)(wid * 32 + r32) * LDQ + hi * 8;
; #pragma unroll
;       for (int d0 = 0; d0 < NQR; ++d0) qr[d0] = *(const bf16x8*)(Qw + d0 * 16);
; #pragma unroll
;       for (int d0 = NQR; d0 < ND0; ++d0) *(bf16x8*)(QL + (d0 - NQR) * 8192) = *(const bf16x8*)(Qw + d0 * 16); }
;     const int sr = tid >> 4, sc = (tid & 15) * 8, vst0 = v_st(sr, sc), vst1 = v_st(32 + sr, sc);
;     const int vb0 = (int)(uintptr_t)V_lds + v_rd_base(lane);
;     const bf16_t* kptr[KCH]; int kld[KCH], kwo[KCH];
; #pragma unroll
;     for (int c = 0; c < KCH; ++c) { const int idx = tid + c * 512, kr_ = idx / CPR, kc = (idx % CPR) * 8;
;         if (kc < DK1) { kptr[c] = a.Kn + (long)kr_ * LDK + kc; kld[c] = LDK; } else { kptr[c] = a.Kr + (long)kr_ * LDKR + (kc - DK1); kld[c] = LDKR; }
;         kwo[c] = kr_ * KP + ((kc * 2) ^ ((kr_ & 7) << 4)); }
;     struct { bf16x8 vs0, vs1, ks[KCH]; } sr_[SDEPTH];
;     int kb[4];
; #pragma unroll
;     for (int m = 0; m < 4; ++m) kb[m] = r32 * KP + ((m * 32 + hi * 16) ^ ((r32 & 7) << 4));
.LBB0_206:
	s_and_b32 s24, s14, 7
	s_mul_i32 s15, s23, 0xc00
	s_mul_hi_i32 s14, s23, 0xc00
	s_add_u32 s15, s4, s15
	s_addc_u32 s14, s5, s14
	s_mul_i32 s20, s24, 0x180
	s_add_u32 s20, s15, s20
	v_mov_b32_e32 v9, v159
	s_addc_u32 s21, s14, 0
	s_lshl_b32 s14, s24, 9
	v_ashrrev_i32_e32 v0, 1, v9
	v_bfe_u32 v2, v9, 5, 1
	v_bfi_b32 v3, s33, v0, v9
	v_mov_b64_e32 v[0:1], s[20:21]
	v_lshlrev_b32_e32 v8, 4, v9
	v_mad_i64_i32 v[0:1], s[20:21], v3, s77, v[0:1]
	v_lshlrev_b32_e32 v96, 4, v2
	v_lshl_add_u64 v[4:5], v[0:1], 0, v[96:97]
	v_add_u32_e32 v0, 0, v8
	global_load_dwordx4 v[126:129], v[4:5], off
	global_load_dwordx4 v[122:125], v[4:5], off offset:32
	global_load_dwordx4 v[118:121], v[4:5], off offset:64
	global_load_dwordx4 v[114:117], v[4:5], off offset:96
	global_load_dwordx4 v[110:113], v[4:5], off offset:128
	global_load_dwordx4 v[106:109], v[4:5], off offset:160
	global_load_dwordx4 v[102:105], v[4:5], off offset:192
	global_load_dwordx4 v[98:101], v[4:5], off offset:224
	v_add_u32_e32 v181, 0x14800, v0
	global_load_dwordx4 v[64:67], v[4:5], off offset:256
	global_load_dwordx4 v[68:71], v[4:5], off offset:288
	global_load_dwordx4 v[72:75], v[4:5], off offset:320
	global_load_dwordx4 v[76:79], v[4:5], off offset:352
	s_add_u32 s14, s6, s14
	s_addc_u32 s15, s7, 0
	v_mul_hi_i32 v0, v9, s86
	v_lshrrev_b32_e32 v1, 31, v0
	v_ashrrev_i32_e32 v0, 2, v0
	v_add_u32_e32 v0, v0, v1
	v_mul_lo_u32 v1, v0, 24
	v_sub_u32_e32 v10, v9, v1
	v_lshlrev_b32_e32 v2, 3, v10
	v_cmp_lt_i32_e32 vcc, 15, v10
	v_ashrrev_i32_e32 v1, 31, v0
	s_and_saveexec_b64 s[20:21], vcc
	s_xor_b64 s[20:21], exec, s[20:21]
	v_lshlrev_b64 v[4:5], 7, v[0:1]
	v_lshl_add_u64 v[4:5], s[18:19], 0, v[4:5]
	v_mov_b32_e32 v3, v97
	s_movk_i32 s38, 0xff00
	v_lshl_add_u64 v[2:3], v[2:3], 1, v[4:5]
	s_mov_b32 s39, -1
	v_lshl_add_u64 v[162:163], v[2:3], 0, s[38:39]
	s_or_saveexec_b64 s[20:21], s[20:21]
	v_mov_b64_e32 v[164:165], 64
	s_xor_b64 exec, exec, s[20:21]
	v_lshlrev_b64 v[4:5], 12, v[0:1]
	v_lshl_add_u64 v[4:5], s[14:15], 0, v[4:5]
	v_ashrrev_i32_e32 v3, 31, v2
	v_lshl_add_u64 v[162:163], v[2:3], 1, v[4:5]
	v_mov_b64_e32 v[164:165], 0x800
	s_or_b64 exec, exec, s[20:21]
	v_add_u32_e32 v1, 0x200, v9
	v_mul_hi_i32 v2, v1, s86
	v_lshrrev_b32_e32 v3, 31, v2
	v_ashrrev_i32_e32 v2, 2, v2
	v_add_u32_e32 v4, v2, v3
	v_mul_lo_u32 v2, v4, 24
	v_sub_u32_e32 v11, v1, v2
	v_lshlrev_b32_e32 v2, 3, v11
	v_cmp_lt_i32_e32 vcc, 15, v11
	v_ashrrev_i32_e32 v5, 31, v4
	s_and_saveexec_b64 s[20:21], vcc
	s_xor_b64 s[20:21], exec, s[20:21]
	v_lshlrev_b64 v[6:7], 7, v[4:5]
	v_lshl_add_u64 v[6:7], s[18:19], 0, v[6:7]
	v_mov_b32_e32 v3, v97
	s_movk_i32 s38, 0xff00
	v_lshl_add_u64 v[2:3], v[2:3], 1, v[6:7]
	s_mov_b32 s39, -1
	v_lshl_add_u64 v[166:167], v[2:3], 0, s[38:39]
	s_or_saveexec_b64 s[20:21], s[20:21]
	v_mov_b64_e32 v[168:169], 64
	s_xor_b64 exec, exec, s[20:21]
	v_lshlrev_b64 v[6:7], 12, v[4:5]
	v_lshl_add_u64 v[6:7], s[14:15], 0, v[6:7]
	v_ashrrev_i32_e32 v3, 31, v2
	v_lshl_add_u64 v[166:167], v[2:3], 1, v[6:7]
	v_mov_b64_e32 v[168:169], 0x800
	s_or_b64 exec, exec, s[20:21]
	v_add_u32_e32 v1, 0x400, v9
	v_mul_hi_i32 v2, v1, s86
	v_lshrrev_b32_e32 v3, 31, v2
	v_ashrrev_i32_e32 v2, 2, v2
	v_add_u32_e32 v2, v2, v3
	v_mul_lo_u32 v3, v2, 24
	v_sub_u32_e32 v1, v1, v3
	v_lshlrev_b32_e32 v6, 3, v1
	v_cmp_lt_i32_e32 vcc, 15, v1
	v_ashrrev_i32_e32 v3, 31, v2
	s_and_saveexec_b64 s[20:21], vcc
	s_xor_b64 s[20:21], exec, s[20:21]
	v_lshlrev_b64 v[12:13], 7, v[2:3]
	v_lshl_add_u64 v[12:13], s[18:19], 0, v[12:13]
	v_mov_b32_e32 v7, v97
	s_movk_i32 s38, 0xff00
	v_lshl_add_u64 v[6:7], v[6:7], 1, v[12:13]
	s_mov_b32 s39, -1
	v_lshl_add_u64 v[170:171], v[6:7], 0, s[38:39]
	s_or_saveexec_b64 s[20:21], s[20:21]
	v_mov_b64_e32 v[172:173], 64
	s_xor_b64 exec, exec, s[20:21]
	v_lshlrev_b64 v[12:13], 12, v[2:3]
	v_lshl_add_u64 v[12:13], s[14:15], 0, v[12:13]
	v_ashrrev_i32_e32 v7, 31, v6
	v_lshl_add_u64 v[170:171], v[6:7], 1, v[12:13]
	v_mov_b64_e32 v[172:173], 0x800
	s_or_b64 exec, exec, s[20:21]
	v_mul_lo_u32 v3, v4, s84
	v_bitop3_b32 v4, v4, v11, 7 bitop3:0x6c
	v_ashrrev_i32_e32 v174, 4, v9
	v_lshl_add_u32 v20, v4, 4, v3
	v_and_b32_e32 v4, 0xfffff0, v174
	v_lshlrev_b32_e32 v5, 1, v174
	v_and_or_b32 v4, v5, 8, v4
	v_lshrrev_b32_e32 v5, 1, v174
	v_and_b32_e32 v6, 3, v174
	v_mul_lo_u32 v3, v0, s84
	v_bitop3_b32 v0, v0, v10, 7 bitop3:0x6c
	v_and_or_b32 v5, v5, 4, v6
	v_add_u32_e32 v6, 32, v174
	v_lshl_add_u32 v21, v0, 4, v3
	v_and_b32_e32 v0, 0x3fffffc0, v9
	s_add_i32 s20, 0, 0x14000
	v_and_b32_e32 v7, 0xfffff0, v6
	v_lshlrev_b32_e32 v6, 1, v6
	v_and_b32_e32 v52, 63, v9
	v_lshl_add_u32 v161, v0, 2, s20
	v_lshlrev_b32_e32 v0, 3, v9
	v_and_or_b32 v6, v6, 8, v7
	v_and_b32_e32 v3, 0x78, v0
	v_lshrrev_b32_e32 v4, 1, v4
	v_bfe_u32 v0, v0, 5, 2
	v_lshrrev_b32_e32 v6, 1, v6
	v_lshlrev_b32_e32 v7, 4, v52
	v_and_b32_e32 v51, 31, v9
	v_or_b32_e32 v4, v4, v0
	v_or_b32_e32 v0, v6, v0
	v_lshlrev_b32_e32 v6, 3, v52
	v_and_b32_e32 v7, 0xc0, v7
	v_lshlrev_b32_e32 v9, 1, v52
	v_and_or_b32 v7, v6, 24, v7
	v_and_b32_e32 v9, 32, v9
	v_and_b32_e32 v6, 0x100, v6
	v_or3_b32 v53, v7, v9, v6
	v_mul_lo_u32 v6, v2, s84
	v_bitop3_b32 v1, v2, v1, 7 bitop3:0x6c
	s_lshl_b32 s20, s68, 6
	v_lshlrev_b32_e32 v5, 6, v5
	v_lshlrev_b32_e32 v0, 9, v0
	v_lshl_add_u32 v22, v1, 4, v6
	v_and_b32_e32 v1, 48, v8
	s_sub_i32 s20, s28, s20
	v_or3_b32 v23, v0, v5, v1
	v_mul_u32_u24_e32 v0, 0x180, v51
	v_and_b32_e32 v2, 0x70, v8
	v_or_b32_e32 v6, 32, v96
	s_and_b64 s[12:13], s[12:13], exec
	v_bitop3_b32 v50, v6, v0, v2 bitop3:0xde
	v_or_b32_e32 v6, 64, v96
	s_cselect_b32 s12, s25, s20
	v_ashrrev_i32_e32 v175, 31, v174
	v_lshlrev_b32_e32 v4, 9, v4
	v_bitop3_b32 v62, v6, v0, v2 bitop3:0xde
	v_or_b32_e32 v6, 0x60, v96
	s_ashr_i32 s13, s12, 31
	v_lshl_add_u64 v[176:177], v[174:175], 0, 32
	v_bitop3_b32 v24, v96, v0, v2 bitop3:0xde
	v_bitop3_b32 v63, v6, v0, v2 bitop3:0xde
	v_or3_b32 v25, v4, v5, v1
	v_lshl_add_u64 v[0:1], v[174:175], 0, s[12:13]
	v_lshl_add_u64 v[4:5], v[176:177], 0, s[12:13]
	v_lshlrev_b64 v[0:1], 12, v[0:1]
	v_lshlrev_b64 v[4:5], 12, v[4:5]
	v_lshl_add_u64 v[0:1], s[14:15], 0, v[0:1]
	v_lshlrev_b32_e32 v48, 1, v3
	v_mov_b32_e32 v49, v97
	v_lshl_add_u64 v[4:5], s[14:15], 0, v[4:5]
	v_mad_i64_i32 v[8:9], s[20:21], v164, s12, 0
	v_mad_i64_i32 v[12:13], s[20:21], v168, s12, 0
	v_mad_i64_i32 v[16:17], s[20:21], v172, s12, 0
	v_lshl_add_u64 v[0:1], v[0:1], 0, v[48:49]
	v_lshl_add_u64 v[4:5], v[4:5], 0, v[48:49]
	v_lshl_add_u64 v[8:9], v[8:9], 1, v[162:163]
	v_lshl_add_u64 v[12:13], v[12:13], 1, v[166:167]
	v_lshl_add_u64 v[16:17], v[16:17], 1, v[170:171]
	global_load_dwordx4 v[0:3], v[0:1], off offset:256
	v_add_u32_e32 v186, 0, v25
	global_load_dwordx4 v[4:7], v[4:5], off offset:256
	v_add_u32_e32 v188, 0, v23
	global_load_dwordx4 v[8:11], v[8:9], off
	v_add_u32_e32 v194, 0, v21
	global_load_dwordx4 v[12:15], v[12:13], off
	v_add_u32_e32 v196, 0, v20
	global_load_dwordx4 v[16:19], v[16:17], off
	v_add_u32_e32 v198, 0, v22
	v_add_u32_e32 v184, 0, v24
	s_waitcnt vmcnt(0)
; #define SLOAD(i, j) do { const long rb_ = KROW(j); sr_[i].vs0 = *(const bf16x8*)(a.V + (rb_ + sr) * LDV + sc); sr_[i].vs1 = *(const bf16x8*)(a.V + (rb_ + 32 + sr) * LDV + sc); \
;     _Pragma("unroll") for (int c_ = 0; c_ < KCH; ++c_) sr_[i].ks[c_] = *(const bf16x8*)(kptr[c_] + rb_ * kld[c_]); } while (0)
; #define SWRITE(b, i) do { *(bf16x8*)(V_lds + (b) * SHM_V + vst0) = sr_[i].vs0; *(bf16x8*)(V_lds + (b) * SHM_V + vst1) = sr_[i].vs1; \
;     _Pragma("unroll") for (int c_ = 0; c_ < KCH; ++c_) *(bf16x8*)(K_lds + (b) * SHM_K + kwo[c_]) = sr_[i].ks[c_]; } while (0)
; template <int DQK, int DK1, int LDQ, int LDK, int LDKR, int LDV, int NQL, int SDEPTH>
; __device__ __forceinline__ void attn_core(const AttnArgs& a, char* lds, f32x16 (&o)[4]) {
;     ...
;     f32x16 pA0, pA1, pB0, pB1; float mnA, mnB, alA, alB; bf16x8 pa0, pa1, pa2, pa3; const int NT = a.NT;
;     constexpr int SE = 0, SO = SDEPTH - 1;
;     SLOAD(SE, 0); asm volatile("s_waitcnt vmcnt(0)" ::: "memory"); SWRITE(0, SE); __syncthreads();
;     QKT(pA0, pA1, K_lds); partialSM(pA0, pA1, m_reg, mnA, alA, a.C, a.thr);
	v_add_u32_e32 v192, 0, v50
	v_add_u32_e32 v190, 0, v62
	v_add_u32_e32 v173, 0, v63
	s_mov_b32 s37, s36
	s_mov_b32 s38, s36
	s_mov_b32 s39, s36
	s_mov_b32 s40, s36
	s_mov_b32 s41, s36
	s_mov_b32 s42, s36
	s_mov_b32 s43, s36
	s_mov_b32 s44, s36
	s_mov_b32 s45, s36
	s_mov_b32 s46, s36
	s_mov_b32 s47, s36
	s_mov_b32 s48, s36
	s_mov_b32 s49, s36
	s_mov_b32 s50, s36
	s_mov_b32 s51, s36
	v_lshl_add_u32 v165, v51, 2, v161
	v_lshl_add_u64 v[178:179], s[14:15], 0, v[48:49]
	s_mov_b32 s69, 2
	v_add_u32_e32 v216, 0xe000, v184
	v_add_u32_e32 v208, 0xe000, v192
	v_add_u32_e32 v206, 0xe000, v190
	v_add_u32_e32 v202, 0xe000, v173
	v_mov_b32_e32 v182, 0
	s_waitcnt vmcnt(0)
	ds_write_b128 v181, v[64:67]
	ds_write_b128 v181, v[68:71] offset:8192
	ds_write_b128 v181, v[72:75] offset:16384
	ds_write_b128 v181, v[76:79] offset:24576
	ds_write_b128 v186, v[0:3]
	ds_write_b128 v188, v[4:7]
	ds_write_b128 v194, v[8:11] offset:32768
	ds_write_b128 v196, v[12:15] offset:32768
	v_mov_b64_e32 v[0:1], s[36:37]
	ds_write_b128 v198, v[16:19] offset:32768
	s_waitcnt lgkmcnt(0)
	s_barrier
	ds_read_b128 v[16:19], v184 offset:32768
	ds_read_b128 v[20:23], v184 offset:45056
	s_waitcnt lgkmcnt(1)
	v_mfma_f32_32x32x16_bf16 v[32:47], v[16:19], v[126:129], 0
	ds_read_b128 v[54:57], v192 offset:32768
	ds_read_b128 v[58:61], v192 offset:45056
	v_mov_b64_e32 v[14:15], s[50:51]
	v_mov_b64_e32 v[2:3], s[38:39]
	v_mov_b64_e32 v[4:5], s[40:41]
	v_mov_b64_e32 v[6:7], s[42:43]
	v_mov_b64_e32 v[8:9], s[44:45]
	v_mov_b64_e32 v[10:11], s[46:47]
	s_waitcnt lgkmcnt(2)
	v_mfma_f32_32x32x16_bf16 v[16:31], v[20:23], v[126:129], 0
	v_mov_b64_e32 v[12:13], s[48:49]
	s_movk_i32 s37, 0x80
	s_waitcnt lgkmcnt(1)
	v_mfma_f32_32x32x16_bf16 v[32:47], v[54:57], v[122:125], v[32:47]
	s_waitcnt lgkmcnt(0)
	v_mfma_f32_32x32x16_bf16 v[16:31], v[58:61], v[122:125], v[16:31]
	ds_read_b128 v[54:57], v190 offset:32768
	ds_read_b128 v[58:61], v190 offset:45056
	s_waitcnt lgkmcnt(1)
	v_mfma_f32_32x32x16_bf16 v[32:47], v[54:57], v[118:121], v[32:47]
	s_waitcnt lgkmcnt(0)
	v_mfma_f32_32x32x16_bf16 v[16:31], v[58:61], v[118:121], v[16:31]
	ds_read_b128 v[54:57], v173 offset:32768
	ds_read_b128 v[58:61], v173 offset:45056
	s_waitcnt lgkmcnt(1)
	v_mfma_f32_32x32x16_bf16 v[32:47], v[54:57], v[114:117], v[32:47]
	s_waitcnt lgkmcnt(0)
	v_mfma_f32_32x32x16_bf16 v[16:31], v[58:61], v[114:117], v[16:31]
	ds_read_b128 v[54:57], v184 offset:32896
	ds_read_b128 v[58:61], v184 offset:45184
	s_waitcnt lgkmcnt(1)
	v_mfma_f32_32x32x16_bf16 v[32:47], v[54:57], v[110:113], v[32:47]
	s_waitcnt lgkmcnt(0)
	v_mfma_f32_32x32x16_bf16 v[16:31], v[58:61], v[110:113], v[16:31]
	ds_read_b128 v[54:57], v192 offset:32896
	ds_read_b128 v[58:61], v192 offset:45184
	s_waitcnt lgkmcnt(1)
	v_mfma_f32_32x32x16_bf16 v[32:47], v[54:57], v[106:109], v[32:47]
	s_waitcnt lgkmcnt(0)
	v_mfma_f32_32x32x16_bf16 v[16:31], v[58:61], v[106:109], v[16:31]
	ds_read_b128 v[54:57], v190 offset:32896
	ds_read_b128 v[58:61], v190 offset:45184
	s_waitcnt lgkmcnt(1)
	v_mfma_f32_32x32x16_bf16 v[32:47], v[54:57], v[102:105], v[32:47]
	s_waitcnt lgkmcnt(0)
	v_mfma_f32_32x32x16_bf16 v[16:31], v[58:61], v[102:105], v[16:31]
	ds_read_b128 v[54:57], v173 offset:32896
	ds_read_b128 v[58:61], v173 offset:45184
	s_waitcnt lgkmcnt(1)
	v_mfma_f32_32x32x16_bf16 v[32:47], v[54:57], v[98:101], v[32:47]
	s_waitcnt lgkmcnt(0)
	v_mfma_f32_32x32x16_bf16 v[16:31], v[58:61], v[98:101], v[16:31]
	ds_read_b128 v[54:57], v184 offset:33024
	ds_read_b128 v[58:61], v184 offset:45312
	ds_read_b128 v[62:65], v181
	s_waitcnt lgkmcnt(0)
	v_mfma_f32_32x32x16_bf16 v[32:47], v[54:57], v[62:65], v[32:47]
	v_mfma_f32_32x32x16_bf16 v[16:31], v[58:61], v[62:65], v[16:31]
	ds_read_b128 v[54:57], v192 offset:33024
	ds_read_b128 v[58:61], v192 offset:45312
	ds_read_b128 v[62:65], v181 offset:8192
	s_waitcnt lgkmcnt(0)
	v_mfma_f32_32x32x16_bf16 v[32:47], v[54:57], v[62:65], v[32:47]
	v_mfma_f32_32x32x16_bf16 v[16:31], v[58:61], v[62:65], v[16:31]
	ds_read_b128 v[54:57], v190 offset:33024
	ds_read_b128 v[58:61], v190 offset:45312
	ds_read_b128 v[62:65], v181 offset:16384
	s_waitcnt lgkmcnt(0)
	v_mfma_f32_32x32x16_bf16 v[32:47], v[54:57], v[62:65], v[32:47]
	v_mfma_f32_32x32x16_bf16 v[16:31], v[58:61], v[62:65], v[16:31]
	ds_read_b128 v[54:57], v173 offset:33024
	ds_read_b128 v[58:61], v173 offset:45312
	ds_read_b128 v[62:65], v181 offset:24576
	s_waitcnt lgkmcnt(0)
; #define SLOAD(i, j) do { const long rb_ = KROW(j); sr_[i].vs0 = *(const bf16x8*)(a.V + (rb_ + sr) * LDV + sc); sr_[i].vs1 = *(const bf16x8*)(a.V + (rb_ + 32 + sr) * LDV + sc); \
;     _Pragma("unroll") for (int c_ = 0; c_ < KCH; ++c_) sr_[i].ks[c_] = *(const bf16x8*)(kptr[c_] + rb_ * kld[c_]); } while (0)
; #define SWRITE(b, i) do { *(bf16x8*)(V_lds + (b) * SHM_V + vst0) = sr_[i].vs0; *(bf16x8*)(V_lds + (b) * SHM_V + vst1) = sr_[i].vs1; \
;     _Pragma("unroll") for (int c_ = 0; c_ < KCH; ++c_) *(bf16x8*)(K_lds + (b) * SHM_K + kwo[c_]) = sr_[i].ks[c_]; } while (0)
; __device__ __forceinline__ void partialSM(f32x16& p0, f32x16& p1, float& m_reg, float& mn, float& alpha, const float C, const float thr) {
;     float pmax = p0[0];
; #pragma unroll
;     for (int r = 1; r < 16; ++r) pmax = fmaxf(pmax, p0[r]);
; #pragma unroll
;     for (int r = 0; r < 16; ++r) pmax = fmaxf(pmax, p1[r]);
;     { auto rr = __builtin_amdgcn_permlane32_swap(__float_as_uint(pmax), __float_as_uint(pmax), false, false);
;       pmax = fmaxf(__uint_as_float(rr[0]), __uint_as_float(rr[1])); }
;     if (__builtin_expect(__all(pmax - m_reg <= thr), 1)) { mn = m_reg; alpha = 1.f; }
;     else { mn = fmaxf(m_reg, pmax); alpha = __builtin_amdgcn_exp2f((m_reg - mn) * C); m_reg = mn; }
;     const float mnC = -mn * C;
; #pragma unroll
;     for (int r = 0; r < 16; ++r) p0[r] = fmaf(p0[r], C, mnC);
; #pragma unroll
;     for (int r = 0; r < 16; ++r) p1[r] = fmaf(p1[r], C, mnC);
; #pragma unroll
;     for (int r = 0; r < 16; ++r) p0[r] = __builtin_amdgcn_exp2f(p0[r]);
; }
; template <int DQK, int DK1, int LDQ, int LDK, int LDKR, int LDV, int NQL, int SDEPTH>
; __device__ __forceinline__ void attn_core(const AttnArgs& a, char* lds, f32x16 (&o)[4]) {
;     ...
;     SLOAD(SO, 1); if (SDEPTH == 2 && 2 < NT) SLOAD(SE, 2);
;     SWRITE(1, SO); __syncthreads();
	v_mfma_f32_32x32x16_bf16 v[32:47], v[54:57], v[62:65], v[32:47]
	v_mfma_f32_32x32x16_bf16 v[16:31], v[58:61], v[62:65], v[16:31]
	s_nop 10
	v_max_f32_e32 v50, v33, v33
	v_max_f32_e32 v54, v32, v32
	v_max_f32_e32 v50, v54, v50
	v_max3_f32 v50, v50, v34, v35
	v_max3_f32 v50, v50, v36, v37
	v_max3_f32 v50, v50, v38, v39
	v_max3_f32 v50, v50, v40, v41
	v_max3_f32 v50, v50, v42, v43
	v_max3_f32 v50, v50, v44, v45
	v_max3_f32 v50, v50, v46, v47
	v_max3_f32 v50, v50, v16, v17
	v_max3_f32 v50, v50, v18, v19
	v_max3_f32 v50, v50, v20, v21
	v_max3_f32 v50, v50, v22, v23
	v_max3_f32 v50, v50, v24, v25
	v_max3_f32 v50, v50, v26, v27
	v_max3_f32 v50, v50, v28, v29
	v_max3_f32 v50, v50, v30, v31
	v_mov_b32_e32 v54, v50
	s_nop 1
	v_permlane32_swap_b32_e32 v50, v54
	v_max_f32_e32 v54, v54, v54
	v_max_f32_e32 v50, v50, v50
	v_max_f32_e32 v50, v50, v54
	v_add_f32_e32 v54, 0x7149f2ca, v50
	v_cmp_ge_f32_e32 vcc, s72, v54
	s_cmp_eq_u64 vcc, exec
	s_cselect_b64 vcc, -1, 0
	v_max_f32_e32 v50, 0xf149f2ca, v50
	v_cndmask_b32_e32 v204, v50, v193, vcc
	v_sub_f32_e32 v54, 0xf149f2ca, v50
	v_mul_f32_e32 v50, 0xbdd53b94, v204
	s_or_b32 s12, s12, 64
	v_fmamk_f32 v32, v32, 0x3dd53b94, v50
	v_fmamk_f32 v33, v33, 0x3dd53b94, v50
	s_ashr_i32 s13, s12, 31
	v_fmamk_f32 v36, v36, 0x3dd53b94, v50
	v_fmamk_f32 v37, v37, 0x3dd53b94, v50
	v_exp_f32_e32 v219, v32
	v_exp_f32_e32 v221, v33
	v_lshl_add_u64 v[32:33], v[174:175], 0, s[12:13]
	v_exp_f32_e32 v156, v36
	v_exp_f32_e32 v218, v37
	v_lshlrev_b64 v[32:33], 12, v[32:33]
	v_lshl_add_u64 v[36:37], v[176:177], 0, s[12:13]
	v_lshl_add_u64 v[32:33], s[14:15], 0, v[32:33]
	v_lshlrev_b64 v[36:37], 12, v[36:37]
	v_fmamk_f32 v34, v34, 0x3dd53b94, v50
	v_fmamk_f32 v35, v35, 0x3dd53b94, v50
	v_fmamk_f32 v40, v40, 0x3dd53b94, v50
	v_fmamk_f32 v41, v41, 0x3dd53b94, v50
	v_lshl_add_u64 v[32:33], v[32:33], 0, v[48:49]
	v_lshl_add_u64 v[36:37], s[14:15], 0, v[36:37]
	v_fmamk_f32 v38, v38, 0x3dd53b94, v50
	v_fmamk_f32 v39, v39, 0x3dd53b94, v50
	v_fmamk_f32 v44, v44, 0x3dd53b94, v50
	v_fmamk_f32 v45, v45, 0x3dd53b94, v50
	v_exp_f32_e32 v157, v34
	v_exp_f32_e32 v220, v35
	v_exp_f32_e32 v151, v40
	v_exp_f32_e32 v153, v41
	global_load_dwordx4 v[32:35], v[32:33], off offset:256
	v_lshl_add_u64 v[36:37], v[36:37], 0, v[48:49]
	v_mad_i64_i32 v[40:41], s[20:21], v164, s12, 0
	v_fmamk_f32 v42, v42, 0x3dd53b94, v50
	v_fmamk_f32 v43, v43, 0x3dd53b94, v50
	v_exp_f32_e32 v154, v38
	v_exp_f32_e32 v155, v39
	v_exp_f32_e32 v147, v44
	v_exp_f32_e32 v149, v45
	global_load_dwordx4 v[36:39], v[36:37], off offset:256
	v_lshl_add_u64 v[40:41], v[40:41], 1, v[162:163]
	v_mad_i64_i32 v[44:45], s[20:21], v168, s12, 0
	v_mul_f32_e32 v58, 0x3dd53b94, v54
	v_fmamk_f32 v46, v46, 0x3dd53b94, v50
	v_fmamk_f32 v47, v47, 0x3dd53b94, v50
	v_exp_f32_e32 v150, v42
	v_exp_f32_e32 v152, v43
	global_load_dwordx4 v[40:43], v[40:41], off
	v_lshl_add_u64 v[44:45], v[44:45], 1, v[166:167]
	v_mad_i64_i32 v[54:55], s[12:13], v172, s12, 0
	v_exp_f32_e32 v146, v46
	v_exp_f32_e32 v148, v47
	global_load_dwordx4 v[44:47], v[44:45], off
	v_lshl_add_u64 v[54:55], v[54:55], 1, v[170:171]
	global_load_dwordx4 v[54:57], v[54:55], off
	v_exp_f32_e32 v58, v58
	s_cmp_lg_u32 0, -1
	s_cselect_b32 s20, 0, 0
	v_add_u32_e32 v200, s20, v53
	s_addk_i32 s20, 0x4000
	s_waitcnt vmcnt(4)
	ds_write_b128 v186, v[32:35] offset:16384
	s_waitcnt vmcnt(3)
	ds_write_b128 v188, v[36:39] offset:16384
	s_waitcnt vmcnt(2)
	ds_write_b128 v194, v[40:43] offset:57344
	s_waitcnt vmcnt(1)
	ds_write_b128 v196, v[44:47] offset:57344
	s_waitcnt vmcnt(0)
	ds_write_b128 v198, v[54:57] offset:57344
	v_cndmask_b32_e64 v217, v58, 1.0, vcc
	v_pk_fma_f32 v[136:137], v[30:31], s[60:61], v[50:51] op_sel_hi:[1,0,0]
	v_pk_fma_f32 v[138:139], v[28:29], s[60:61], v[50:51] op_sel_hi:[1,0,0]
	v_pk_fma_f32 v[144:145], v[26:27], s[60:61], v[50:51] op_sel_hi:[1,0,0]
	v_pk_fma_f32 v[130:131], v[24:25], s[60:61], v[50:51] op_sel_hi:[1,0,0]
	v_pk_fma_f32 v[132:133], v[22:23], s[60:61], v[50:51] op_sel_hi:[1,0,0]
	v_pk_fma_f32 v[134:135], v[20:21], s[60:61], v[50:51] op_sel_hi:[1,0,0]
	v_pk_fma_f32 v[140:141], v[18:19], s[60:61], v[50:51] op_sel_hi:[1,0,0]
	v_pk_fma_f32 v[142:143], v[16:17], s[60:61], v[50:51] op_sel_hi:[1,0,0]
	v_cmp_gt_u32_e64 s[12:13], 32, v52
	v_add_u32_e32 v169, s20, v53
	v_mov_b64_e32 v[30:31], v[14:15]
	v_mov_b64_e32 v[46:47], v[14:15]
	v_mov_b64_e32 v[62:63], v[14:15]
	v_mov_b64_e32 v[28:29], v[12:13]
	v_mov_b64_e32 v[26:27], v[10:11]
	v_mov_b64_e32 v[24:25], v[8:9]
	v_mov_b64_e32 v[22:23], v[6:7]
	v_mov_b64_e32 v[20:21], v[4:5]
	v_mov_b64_e32 v[18:19], v[2:3]
	v_mov_b64_e32 v[16:17], v[0:1]
	v_mov_b64_e32 v[44:45], v[12:13]
	v_mov_b64_e32 v[42:43], v[10:11]
	v_mov_b64_e32 v[40:41], v[8:9]
	v_mov_b64_e32 v[38:39], v[6:7]
	v_mov_b64_e32 v[36:37], v[4:5]
	v_mov_b64_e32 v[34:35], v[2:3]
	v_mov_b64_e32 v[32:33], v[0:1]
	v_mov_b64_e32 v[60:61], v[12:13]
	v_mov_b64_e32 v[58:59], v[10:11]
	v_mov_b64_e32 v[56:57], v[8:9]
	v_mov_b64_e32 v[54:55], v[6:7]
	v_mov_b64_e32 v[52:53], v[4:5]
	v_mov_b64_e32 v[50:51], v[2:3]
	v_mov_b64_e32 v[48:49], v[0:1]
	v_readfirstlane_b32 s98, v159
	s_nop 3
	s_cmp_gt_u32 s98, 0xff
	s_cbranch_scc0 .Lsprio_m
	s_setprio 1

; __device__ __forceinline__ void finishSM(f32x16& p0, f32x16& p1, float alpha, float& l_reg, bf16x8& pa0, bf16x8& pa1, bf16x8& pa2, bf16x8& pa3) {
; #pragma unroll
;     for (int r = 0; r < 16; ++r) p1[r] = __builtin_amdgcn_exp2f(p1[r]);
;     float ps = 0;
; #pragma unroll
;     for (int r = 0; r < 16; ++r) ps += p0[r];
; #pragma unroll
;     for (int r = 0; r < 16; ++r) ps += p1[r];
;     { auto rr = __builtin_amdgcn_permlane32_swap(__float_as_uint(ps), __float_as_uint(ps), false, false);
;       ps = __uint_as_float(rr[0]) + __uint_as_float(rr[1]); }
;     l_reg = l_reg * alpha + ps;
;     ...
;     PK4(p0, 0, pa0); PK4(p0, 8, pa1); PK4(p1, 0, pa2); PK4(p1, 8, pa3);
;     ...
; }
.LBB0_229:
	s_setprio 0
	ds_read_b128 v[64:67], v184 offset:57344
	ds_read_b128 v[68:71], v216 offset:12288
	s_waitcnt lgkmcnt(1)
	v_mfma_f32_32x32x16_bf16 v[80:95], v[64:67], v[126:129], 0
	s_waitcnt lgkmcnt(0)
	v_mfma_f32_32x32x16_bf16 v[64:79], v[68:71], v[126:129], 0
	ds_read_b128 v[126:129], v192 offset:57344
	ds_read_b128 v[174:177], v208 offset:12288
	s_waitcnt lgkmcnt(1)
	v_mfma_f32_32x32x16_bf16 v[80:95], v[126:129], v[122:125], v[80:95]
	s_waitcnt lgkmcnt(0)
	v_mfma_f32_32x32x16_bf16 v[64:79], v[174:177], v[122:125], v[64:79]
	ds_read_b128 v[122:125], v190 offset:57344
	ds_read_b128 v[126:129], v206 offset:12288
	s_waitcnt lgkmcnt(1)
	v_mfma_f32_32x32x16_bf16 v[80:95], v[122:125], v[118:121], v[80:95]
	s_waitcnt lgkmcnt(0)
	v_mfma_f32_32x32x16_bf16 v[64:79], v[126:129], v[118:121], v[64:79]
	ds_read_b128 v[118:121], v173 offset:57344
	ds_read_b128 v[122:125], v202 offset:12288
	s_waitcnt lgkmcnt(1)
	v_mfma_f32_32x32x16_bf16 v[80:95], v[118:121], v[114:117], v[80:95]
	s_waitcnt lgkmcnt(0)
	v_mfma_f32_32x32x16_bf16 v[64:79], v[122:125], v[114:117], v[64:79]
	ds_read_b128 v[114:117], v184 offset:57472
	ds_read_b128 v[118:121], v216 offset:12416
	v_exp_f32_e32 v122, v136
	v_exp_f32_e32 v123, v137
	s_waitcnt lgkmcnt(1)
	v_mfma_f32_32x32x16_bf16 v[80:95], v[114:117], v[110:113], v[80:95]
	s_waitcnt lgkmcnt(0)
	v_mfma_f32_32x32x16_bf16 v[64:79], v[118:121], v[110:113], v[64:79]
	ds_read_b128 v[110:113], v192 offset:57472
	ds_read_b128 v[114:117], v208 offset:12416
	v_exp_f32_e32 v118, v144
	v_exp_f32_e32 v119, v145
	v_exp_f32_e32 v120, v138
	v_exp_f32_e32 v121, v139
	s_waitcnt lgkmcnt(1)
	v_mfma_f32_32x32x16_bf16 v[80:95], v[110:113], v[106:109], v[80:95]
	s_waitcnt lgkmcnt(0)
	v_mfma_f32_32x32x16_bf16 v[64:79], v[114:117], v[106:109], v[64:79]
	ds_read_b128 v[106:109], v190 offset:57472
	ds_read_b128 v[110:113], v206 offset:12416
	v_exp_f32_e32 v114, v132
	v_exp_f32_e32 v115, v133
	v_exp_f32_e32 v116, v130
	v_exp_f32_e32 v117, v131
	s_waitcnt lgkmcnt(1)
	v_mfma_f32_32x32x16_bf16 v[80:95], v[106:109], v[102:105], v[80:95]
	s_waitcnt lgkmcnt(0)
	v_mfma_f32_32x32x16_bf16 v[64:79], v[110:113], v[102:105], v[64:79]
	ds_read_b128 v[102:105], v173 offset:57472
	ds_read_b128 v[106:109], v202 offset:12416
	v_exp_f32_e32 v110, v140
	v_exp_f32_e32 v111, v141
	v_exp_f32_e32 v112, v134
	v_exp_f32_e32 v113, v135
	s_waitcnt lgkmcnt(1)
	v_mfma_f32_32x32x16_bf16 v[80:95], v[102:105], v[98:101], v[80:95]
	s_waitcnt lgkmcnt(0)
	v_mfma_f32_32x32x16_bf16 v[64:79], v[106:109], v[98:101], v[64:79]
	ds_read_b128 v[98:101], v184 offset:57600
	ds_read_b128 v[102:105], v216 offset:12544
	ds_read_b128 v[106:109], v181
	s_waitcnt lgkmcnt(0)
	v_mfma_f32_32x32x16_bf16 v[80:95], v[98:101], v[106:109], v[80:95]
	v_mfma_f32_32x32x16_bf16 v[64:79], v[102:105], v[106:109], v[64:79]
	ds_read_b128 v[98:101], v192 offset:57600
	ds_read_b128 v[102:105], v208 offset:12544
	ds_read_b128 v[106:109], v181 offset:8192
	s_waitcnt lgkmcnt(0)
	v_mfma_f32_32x32x16_bf16 v[80:95], v[98:101], v[106:109], v[80:95]
	v_mfma_f32_32x32x16_bf16 v[64:79], v[102:105], v[106:109], v[64:79]
	ds_read_b128 v[98:101], v190 offset:57600
	ds_read_b128 v[102:105], v206 offset:12544
	ds_read_b128 v[106:109], v181 offset:16384
	s_waitcnt lgkmcnt(0)
	v_mfma_f32_32x32x16_bf16 v[80:95], v[98:101], v[106:109], v[80:95]
	v_mfma_f32_32x32x16_bf16 v[64:79], v[102:105], v[106:109], v[64:79]
	ds_read_b128 v[98:101], v173 offset:57600
	ds_read_b128 v[102:105], v202 offset:12544
	ds_read_b128 v[106:109], v181 offset:24576
	s_waitcnt lgkmcnt(0)
	v_mfma_f32_32x32x16_bf16 v[80:95], v[98:101], v[106:109], v[80:95]
	v_add_f32_e32 v98, 0, v219
	v_add_f32_e32 v98, v221, v98
	v_add_f32_e32 v98, v157, v98
	v_add_f32_e32 v98, v220, v98
	v_add_f32_e32 v98, v156, v98
	v_add_f32_e32 v98, v218, v98
	v_add_f32_e32 v98, v154, v98
	v_add_f32_e32 v98, v155, v98
	v_add_f32_e32 v98, v151, v98
	v_add_f32_e32 v98, v153, v98
	v_add_f32_e32 v98, v150, v98
	v_add_f32_e32 v98, v152, v98
	v_mfma_f32_32x32x16_bf16 v[64:79], v[102:105], v[106:109], v[64:79]
	v_exp_f32_e32 v108, v142
	v_add_f32_e32 v98, v147, v98
	v_exp_f32_e32 v109, v143
	v_add_f32_e32 v98, v149, v98
	v_add_f32_e32 v98, v146, v98
	v_add_f32_e32 v98, v148, v98
	v_add_f32_e32 v98, v108, v98
	v_add_f32_e32 v98, v109, v98
	v_add_f32_e32 v98, v110, v98
	v_add_f32_e32 v98, v111, v98
	v_add_f32_e32 v98, v112, v98
	v_add_f32_e32 v98, v113, v98
	v_add_f32_e32 v98, v114, v98
	v_add_f32_e32 v98, v115, v98
	v_add_f32_e32 v98, v116, v98
	v_add_f32_e32 v98, v117, v98
	v_add_f32_e32 v98, v118, v98
	v_add_f32_e32 v98, v119, v98
	v_add_f32_e32 v98, v120, v98
	v_add_f32_e32 v98, v121, v98
	v_add_f32_e32 v98, v122, v98
	v_add_f32_e32 v102, v123, v98
	v_mov_b32_e32 v103, v102
	v_cvt_pk_bf16_f32 v98, v219, v221
	v_cvt_pk_bf16_f32 v99, v157, v220
	v_cvt_pk_bf16_f32 v100, v156, v218
	v_cvt_pk_bf16_f32 v101, v154, v155
	s_nop 1
	v_permlane32_swap_b32_e32 v102, v103
	v_permlane32_swap_b32_e32 v98, v100
	v_permlane32_swap_b32_e32 v99, v101
	v_cvt_pk_bf16_f32 v104, v151, v153
	v_cvt_pk_bf16_f32 v105, v150, v152
	v_cvt_pk_bf16_f32 v106, v147, v149
	v_cvt_pk_bf16_f32 v107, v146, v148
	v_cvt_pk_bf16_f32 v108, v108, v109
	v_cvt_pk_bf16_f32 v109, v110, v111
	v_cvt_pk_bf16_f32 v110, v112, v113
	v_cvt_pk_bf16_f32 v111, v114, v115
	v_cvt_pk_bf16_f32 v112, v116, v117
	v_cvt_pk_bf16_f32 v113, v118, v119
	v_cvt_pk_bf16_f32 v114, v120, v121
	v_cvt_pk_bf16_f32 v115, v122, v123
	s_nop 0
	v_permlane32_swap_b32_e32 v104, v106
	v_permlane32_swap_b32_e32 v105, v107
	v_permlane32_swap_b32_e32 v108, v110
	v_permlane32_swap_b32_e32 v109, v111
	v_permlane32_swap_b32_e32 v112, v114
	v_permlane32_swap_b32_e32 v113, v115
	ds_read_b64_tr_b16 v[116:117], v200 offset:0
	ds_read_b64_tr_b16 v[118:119], v200 offset:0x800
	ds_read_b64_tr_b16 v[120:121], v200 offset:0x1000
	ds_read_b64_tr_b16 v[122:123], v200 offset:0x1800
	ds_read_b64_tr_b16 v[124:125], v200 offset:0x2000
	ds_read_b64_tr_b16 v[126:127], v200 offset:0x2800
	ds_read_b64_tr_b16 v[128:129], v200 offset:0x3000
	ds_read_b64_tr_b16 v[130:131], v200 offset:0x3800
	s_waitcnt lgkmcnt(0)
; #define SBAR() __builtin_amdgcn_sched_barrier(0)
; template <int OFF> __device__ __forceinline__ s16x4 tr_read(int vb) { s16x4 r; asm volatile("ds_read_b64_tr_b16 %0, %1 offset:%2" : "=&v"(r) : "v"(vb), "i"(OFF) : "memory"); return r; }
; template <int D0> __device__ __forceinline__ void pv_one(f32x16& od, int vb, bf16x8 pa0, bf16x8 pa1, bf16x8 pa2, bf16x8 pa3) {
;     const s16x4 l0 = tr_read<v_rd_off(D0, 0, 0)>(vb), h0 = tr_read<v_rd_off(D0, 0, 1)>(vb), l1 = tr_read<v_rd_off(D0, 1, 0)>(vb), h1 = tr_read<v_rd_off(D0, 1, 1)>(vb);
;     const s16x4 l2 = tr_read<v_rd_off(D0, 2, 0)>(vb), h2 = tr_read<v_rd_off(D0, 2, 1)>(vb), l3 = tr_read<v_rd_off(D0, 3, 0)>(vb), h3 = tr_read<v_rd_off(D0, 3, 1)>(vb);
;     asm volatile("s_waitcnt lgkmcnt(0)" ::: "memory"); SBAR();
;     ...
;     od = __builtin_amdgcn_mfma_f32_32x32x16_bf16(pa0, PK(l0, h0), od, 0, 0, 0);
;     od = __builtin_amdgcn_mfma_f32_32x32x16_bf16(pa1, PK(l1, h1), od, 0, 0, 0);
;     od = __builtin_amdgcn_mfma_f32_32x32x16_bf16(pa2, PK(l2, h2), od, 0, 0, 0);
;     od = __builtin_amdgcn_mfma_f32_32x32x16_bf16(pa3, PK(l3, h3), od, 0, 0, 0);
;     ...
; }
; __device__ __forceinline__ void pv_d0(f32x16* o, int vb, bf16x8 pa0, bf16x8 pa1, bf16x8 pa2, bf16x8 pa3) {
;     pv_one<0>(o[0], vb, pa0, pa1, pa2, pa3); pv_one<1>(o[1], vb, pa0, pa1, pa2, pa3); pv_one<2>(o[2], vb, pa0, pa1, pa2, pa3); pv_one<3>(o[3], vb, pa0, pa1, pa2, pa3);
; }
; __device__ __forceinline__ void partialSM(f32x16& p0, f32x16& p1, float& m_reg, float& mn, float& alpha, const float C, const float thr) {
;     float pmax = p0[0];
; #pragma unroll
;     for (int r = 1; r < 16; ++r) pmax = fmaxf(pmax, p0[r]);
; #pragma unroll
;     for (int r = 0; r < 16; ++r) pmax = fmaxf(pmax, p1[r]);
;     { auto rr = __builtin_amdgcn_permlane32_swap(__float_as_uint(pmax), __float_as_uint(pmax), false, false);
;       pmax = fmaxf(__uint_as_float(rr[0]), __uint_as_float(rr[1])); }
;     if (__builtin_expect(__all(pmax - m_reg <= thr), 1)) { mn = m_reg; alpha = 1.f; }
;     else { mn = fmaxf(m_reg, pmax); alpha = __builtin_amdgcn_exp2f((m_reg - mn) * C); m_reg = mn; }
; template <int DQK, int DK1, int LDQ, int LDK, int LDKR, int LDV, int NQL, int SDEPTH>
; __device__ __forceinline__ void attn_core(const AttnArgs& a, char* lds, f32x16 (&o)[4]) {
;     ...
;     pv_d0(o, vb0, pa0, pa1, pa2, pa3); partialSM(pB0, pB1, m_reg, mnB, alB, a.C, a.thr);
;     __syncthreads(); RESC(alB);
	s_nop 0
	v_mfma_f32_32x32x16_bf16 v[48:63], v[98:101], v[116:119], v[48:63]
	ds_read_b64_tr_b16 v[116:117], v200 offset:0x200
	ds_read_b64_tr_b16 v[118:119], v200 offset:0xa00
	v_mfma_f32_32x32x16_bf16 v[48:63], v[104:107], v[120:123], v[48:63]
	ds_read_b64_tr_b16 v[120:121], v200 offset:0x1200
	ds_read_b64_tr_b16 v[122:123], v200 offset:0x1a00
	v_mfma_f32_32x32x16_bf16 v[48:63], v[108:111], v[124:127], v[48:63]
	ds_read_b64_tr_b16 v[124:125], v200 offset:0x2200
	ds_read_b64_tr_b16 v[126:127], v200 offset:0x2a00
	v_mfma_f32_32x32x16_bf16 v[48:63], v[112:115], v[128:131], v[48:63]
	ds_read_b64_tr_b16 v[128:129], v200 offset:0x3200
	ds_read_b64_tr_b16 v[130:131], v200 offset:0x3a00
	s_waitcnt lgkmcnt(0)
	v_mfma_f32_32x32x16_bf16 v[32:47], v[98:101], v[116:119], v[32:47]
	ds_read_b64_tr_b16 v[116:117], v200 offset:0x400
	ds_read_b64_tr_b16 v[118:119], v200 offset:0xc00
	v_mfma_f32_32x32x16_bf16 v[32:47], v[104:107], v[120:123], v[32:47]
	ds_read_b64_tr_b16 v[120:121], v200 offset:0x1400
	ds_read_b64_tr_b16 v[122:123], v200 offset:0x1c00
	v_mfma_f32_32x32x16_bf16 v[32:47], v[108:111], v[124:127], v[32:47]
	ds_read_b64_tr_b16 v[124:125], v200 offset:0x2400
	ds_read_b64_tr_b16 v[126:127], v200 offset:0x2c00
	v_mfma_f32_32x32x16_bf16 v[32:47], v[112:115], v[128:131], v[32:47]
	ds_read_b64_tr_b16 v[128:129], v200 offset:0x3400
	ds_read_b64_tr_b16 v[130:131], v200 offset:0x3c00
	s_waitcnt lgkmcnt(0)
	v_mfma_f32_32x32x16_bf16 v[16:31], v[98:101], v[116:119], v[16:31]
	ds_read_b64_tr_b16 v[116:117], v200 offset:0x600
	ds_read_b64_tr_b16 v[118:119], v200 offset:0xe00
	v_mfma_f32_32x32x16_bf16 v[16:31], v[104:107], v[120:123], v[16:31]
	ds_read_b64_tr_b16 v[120:121], v200 offset:0x1600
	ds_read_b64_tr_b16 v[122:123], v200 offset:0x1e00
	v_mfma_f32_32x32x16_bf16 v[16:31], v[108:111], v[124:127], v[16:31]
	ds_read_b64_tr_b16 v[124:125], v200 offset:0x2600
	ds_read_b64_tr_b16 v[126:127], v200 offset:0x2e00
	v_mfma_f32_32x32x16_bf16 v[16:31], v[112:115], v[128:131], v[16:31]
	ds_read_b64_tr_b16 v[128:129], v200 offset:0x3600
	ds_read_b64_tr_b16 v[130:131], v200 offset:0x3e00
	s_waitcnt lgkmcnt(0)
	v_mfma_f32_32x32x16_bf16 v[0:15], v[98:101], v[116:119], v[0:15]
	v_max_f32_e32 v98, v81, v81
	v_max_f32_e32 v99, v80, v80
	v_max_f32_e32 v98, v99, v98
	v_max3_f32 v98, v98, v82, v83
	v_max3_f32 v98, v98, v84, v85
	v_max3_f32 v98, v98, v86, v87
	v_max3_f32 v98, v98, v88, v89
	v_max3_f32 v98, v98, v90, v91
	v_max3_f32 v98, v98, v92, v93
	v_mfma_f32_32x32x16_bf16 v[0:15], v[104:107], v[120:123], v[0:15]
	v_max3_f32 v98, v98, v94, v95
	v_max3_f32 v98, v98, v64, v65
	v_max3_f32 v98, v98, v66, v67
	v_max3_f32 v98, v98, v68, v69
	v_max3_f32 v98, v98, v70, v71
	v_max3_f32 v98, v98, v72, v73
	v_max3_f32 v98, v98, v74, v75
	v_max3_f32 v98, v98, v76, v77
	v_mfma_f32_32x32x16_bf16 v[0:15], v[108:111], v[124:127], v[0:15]
	v_max3_f32 v98, v98, v78, v79
	v_mov_b32_e32 v99, v98
	s_nop 1
	v_permlane32_swap_b32_e32 v98, v99
	v_max_f32_e32 v99, v99, v99
	v_max_f32_e32 v98, v98, v98
	v_max_f32_e32 v98, v98, v99
	v_sub_f32_e32 v99, v98, v204
	v_cmp_ge_f32_e32 vcc, s72, v99
	v_max_f32_e32 v99, v204, v204
	v_max_f32_e32 v99, v99, v98
	v_mfma_f32_32x32x16_bf16 v[0:15], v[112:115], v[128:131], v[0:15]
	v_sub_f32_e32 v98, v204, v99
	v_mul_f32_e32 v98, 0x3dd53b94, v98
	v_exp_f32_e32 v98, v98
	s_cmp_eq_u64 vcc, exec
	s_cselect_b64 s[14:15], -1, 0
	v_cndmask_b32_e64 v98, v98, 1.0, s[14:15]
	v_cmp_gt_f32_e32 vcc, 1.0, v98
	s_barrier
	s_cbranch_vccz .LBB0_233
	s_and_saveexec_b64 s[20:21], s[12:13]
	s_movk_i32 s37, 0x7fff
	s_movk_i32 s73, 0x47ff
	v_readlane_b32 s68, v255, 18
	ds_write_b32 v165, v98 offset:128
	s_or_b64 exec, exec, s[20:21]
	s_waitcnt lgkmcnt(0)
	v_add_u32_e32 v100, v161, v96
	ds_read_b128 v[104:107], v100 offset:224
	ds_read_b128 v[108:111], v100 offset:192
	ds_read_b128 v[112:115], v100 offset:160
	ds_read_b128 v[116:119], v100 offset:128
	s_waitcnt lgkmcnt(3)
	v_pk_mul_f32 v[60:61], v[60:61], v[104:105]
	s_waitcnt lgkmcnt(2)
	v_pk_mul_f32 v[56:57], v[56:57], v[108:109]
	s_waitcnt lgkmcnt(1)
	v_pk_mul_f32 v[52:53], v[52:53], v[112:113]
	v_pk_mul_f32 v[62:63], v[62:63], v[106:107]
	v_pk_mul_f32 v[58:59], v[58:59], v[110:111]
	v_pk_mul_f32 v[54:55], v[54:55], v[114:115]
	s_waitcnt lgkmcnt(0)
	v_pk_mul_f32 v[50:51], v[50:51], v[118:119]
	v_pk_mul_f32 v[48:49], v[48:49], v[116:117]
	v_pk_mul_f32 v[44:45], v[44:45], v[104:105]
	v_pk_mul_f32 v[40:41], v[40:41], v[108:109]
	v_pk_mul_f32 v[36:37], v[36:37], v[112:113]
	v_pk_mul_f32 v[46:47], v[46:47], v[106:107]
	v_pk_mul_f32 v[42:43], v[42:43], v[110:111]
	v_pk_mul_f32 v[38:39], v[38:39], v[114:115]
	v_pk_mul_f32 v[34:35], v[34:35], v[118:119]
	v_pk_mul_f32 v[32:33], v[32:33], v[116:117]
	v_pk_mul_f32 v[28:29], v[28:29], v[104:105]
	v_pk_mul_f32 v[24:25], v[24:25], v[108:109]
	v_pk_mul_f32 v[20:21], v[20:21], v[112:113]
	v_pk_mul_f32 v[30:31], v[30:31], v[106:107]
	v_pk_mul_f32 v[26:27], v[26:27], v[110:111]
	v_pk_mul_f32 v[22:23], v[22:23], v[114:115]
	v_pk_mul_f32 v[18:19], v[18:19], v[118:119]
	v_pk_mul_f32 v[16:17], v[16:17], v[116:117]
	v_pk_mul_f32 v[12:13], v[12:13], v[104:105]
	v_pk_mul_f32 v[8:9], v[8:9], v[108:109]
	v_pk_mul_f32 v[4:5], v[4:5], v[112:113]
	v_pk_mul_f32 v[14:15], v[14:15], v[106:107]
	v_pk_mul_f32 v[10:11], v[10:11], v[110:111]
	v_pk_mul_f32 v[6:7], v[6:7], v[114:115]
	v_pk_mul_f32 v[2:3], v[2:3], v[118:119]
	v_pk_mul_f32 v[0:1], v[0:1], v[116:117]
	s_branch .LBB0_234
